# RWKV scan: chunk barrier split (A at token 15 once operands are in registers, B after the y writes) so the next chunk's first operands are fetched during token 15; prep waves execute the barrier pair
# baseline (speedup 1.0000x reference)
; #define LDS_BAR() do { asm volatile("s_waitcnt lgkmcnt(0)" ::: "memory"); __builtin_amdgcn_s_barrier(); asm volatile("" ::: "memory"); } while (0)
; __device__ __forceinline__ void rwkv_block(KP p, int o, int b, int hd, LAS unsigned char* lds, const bf16_t* P, bf16_t* YB) {
;     ...
;         for (int n = 0; n < 256; n += 2) {
;             if (n + 2 < 256) load_rows(n + 2, rawA);
;             if (n >= 1) outp(n - 1);
;             prep(n + 1, rawB);
;             LDS_BAR();
;             if (n + 3 < 256) load_rows(n + 3, rawB);
;             outp(n);
;             if (n + 2 < 256) prep(n + 2, rawA);
;             LDS_BAR();
;         }
.LBB0_203:
	s_waitcnt lgkmcnt(0)
	s_barrier
	s_barrier
	s_add_i32 s1, s1, 2
	s_add_i32 s56, s56, 32
	v_lshl_add_u64 v[130:131], v[130:131], 0, s[36:37]
	s_and_b64 vcc, exec, s[24:25]
	s_cbranch_vccnz .LBB0_231

; #define LAS __attribute__((address_space(3)))
; __device__ __forceinline__ float rcp_(float x) { return __builtin_amdgcn_rcpf(x); }
; __device__ __forceinline__ float sigmoidf_(float x) { return rcp_(1.0f + __expf(-x)); }
; __device__ __forceinline__ float softplus_fast(float x) { return fmaxf(x, 0.f) + __logf(1.0f + __expf(-fabsf(x))); }
; #define LDS_BAR() do { asm volatile("s_waitcnt lgkmcnt(0)" ::: "memory"); __builtin_amdgcn_s_barrier(); asm volatile("" ::: "memory"); } while (0)
; __device__ __forceinline__ void rwkv_block(KP p, int o, int b, int hd, LAS unsigned char* lds, const bf16_t* P, bf16_t* YB) {
;     ...
;             const f32x4 wl = *(const LAS f32x4*)(Lout + t4 * 68 + 4 * jg), al = *(const LAS f32x4*)(Lout + 272 + t4 * 68 + 4 * jg), gg = *(const LAS f32x4*)(Lout + 544 + t4 * 68 + 4 * jg);
;             f32x4 decay, kk, bbv, km;
;             float nsq = 0.f, bon = 0.f;
; #pragma unroll
;             for (int i = 0; i < 4; ++i) {
;                 const float w_raw = -softplus_fast(-(w0[i] + wl[i])) - 0.5f;
;                 decay[i] = __expf(-__expf(w_raw));
;                 const float a = sigmoidf_(a0[i] + al[i]);
;                 kk[i] = k0[i] * k_k[i];
;                 nsq += kk[i] * kk[i];
;                 km[i] = k0[i] * (1.0f + (a - 1.0f) * k_a[i]);
;                 bon += rr[i] * km[i] * r_k[i];
;                 bbv[i] = a;
;             }
;             nsq = red16(nsq); bon = red16(bon);
;             const float inv = rcp_(fmaxf(__builtin_amdgcn_sqrtf(nsq), 1e-12f));
;             kk = kk * inv; bbv = bbv * kk;
;             *(LAS f32x4*)(Wd + tt * 64 + 4 * jg) = decay; *(LAS f32x4*)(KK + tt * 64 + 4 * jg) = -kk; *(LAS f32x4*)(BB + tt * 64 + 4 * jg) = bbv; *(LAS f32x4*)(KM + tt * 64 + 4 * jg) = km;
;             *(LAS f32x4*)(Rr + tt * 64 + 4 * jg) = rr; *(LAS f32x4*)(Vv + tt * 64 + 4 * jg) = vv; *(LAS f32x4*)(Gg + tt * 64 + 4 * jg) = gg;
;             if (jg == 0) Bon[tt] = bon;
;     ...
;             LDS_BAR();
;             if (n + 3 < 256) load_rows(n + 3, rawB);
.LBB0_216:
	s_or_b64 exec, exec, s[18:19]
	s_waitcnt lgkmcnt(0)
	v_lshlrev_b32_e32 v78, 16, v121
	v_and_b32_e32 v79, 0xffff0000, v121
	s_nop 2
	v_lshlrev_b32_e32 v68, 16, v123
	v_and_b32_e32 v69, 0xffff0000, v123
	v_sub_f32_e32 v83, v69, v79
	v_sub_f32_e32 v82, v68, v78
	ds_read_b128 v[68:71], v141 offset:36864
	v_lshlrev_b32_e32 v88, 16, v116
	v_and_b32_e32 v89, 0xffff0000, v116
	v_and_b32_e32 v91, 0xffff0000, v117
	v_lshlrev_b32_e32 v72, 16, v126
	v_and_b32_e32 v73, 0xffff0000, v126
	v_and_b32_e32 v74, 0xffff0000, v127
	v_sub_f32_e32 v93, v73, v89
	v_sub_f32_e32 v92, v72, v88
	v_sub_f32_e32 v95, v74, v91
	ds_read_b128 v[72:75], v141 offset:37952
	s_waitcnt lgkmcnt(1)
	v_add_f32_e32 v68, v32, v68
	v_mul_f32_e64 v164, v68, s68
	v_exp_f32_e32 v167, v164
	v_lshlrev_b32_e32 v76, 16, v120
	v_lshlrev_b32_e32 v0, 16, v122
	v_sub_f32_e32 v80, v0, v76
	v_lshlrev_b32_e32 v84, 16, v118
	v_lshlrev_b32_e32 v0, 16, v124
	v_and_b32_e32 v77, 0xffff0000, v120
	v_and_b32_e32 v3, 0xffff0000, v122
	v_sub_f32_e32 v164, v0, v84
	v_add_f32_e32 v0, 1.0, v167
	v_sub_f32_e32 v81, v3, v77
	v_and_b32_e32 v85, 0xffff0000, v118
	v_and_b32_e32 v3, 0xffff0000, v124
	v_sub_f32_e32 v165, v3, v85
	v_lshlrev_b32_e32 v86, 16, v119
	v_rcp_f32_e32 v0, v0
	v_and_b32_e32 v87, 0xffff0000, v119
	v_lshlrev_b32_e32 v97, 16, v125
	v_and_b32_e32 v166, 0xffff0000, v125
	v_sub_f32_e32 v167, v166, v87
	v_add_f32_e32 v3, v33, v69
	v_mul_f32_e64 v68, v3, s68
	v_exp_f32_e32 v68, v68
	s_waitcnt lgkmcnt(0)
	v_add_f32_e32 v69, v36, v72
	v_add_f32_e32 v68, 1.0, v68
	v_mul_f32_e32 v69, 0xbfb8aa3b, v69
	v_exp_f32_e32 v69, v69
	v_rcp_f32_e32 v3, v68
	v_mul_f32_e32 v0, 0xbf60028b, v0
	v_exp_f32_e32 v68, v0
	v_add_f32_e32 v0, 1.0, v69
	v_rcp_f32_e32 v168, v0
	v_add_f32_e32 v69, v37, v73
	v_mul_f32_e32 v69, 0xbfb8aa3b, v69
	v_exp_f32_e32 v69, v69
	v_sub_f32_e32 v166, v97, v86
	v_add_f32_e32 v0, 1.0, v69
	v_rcp_f32_e32 v169, v0
	v_mul_f32_e32 v0, 0xbf60028b, v3
	v_exp_f32_e32 v69, v0
	v_add_f32_e32 v0, v34, v70
	v_mul_f32_e64 v3, v0, s68
	v_exp_f32_e32 v3, v3
	v_pk_add_f32 v[72:73], v[168:169], -1.0 op_sel_hi:[1,0]
	v_pk_fma_f32 v[84:85], v[8:9], v[164:165], v[84:85]
	v_pk_fma_f32 v[72:73], v[44:45], v[72:73], 1.0 op_sel_hi:[1,1,0]
	v_add_f32_e32 v3, 1.0, v3
	v_pk_fma_f32 v[76:77], v[4:5], v[80:81], v[76:77]
	v_pk_mul_f32 v[72:73], v[84:85], v[72:73]
	v_rcp_f32_e32 v0, v3
	v_mul_f32_e32 v70, v76, v72
	v_fma_f32 v97, v48, v70, 0
	v_pk_fma_f32 v[86:87], v[10:11], v[166:167], v[86:87]
	v_pk_fma_f32 v[78:79], v[6:7], v[82:83], v[78:79]
	v_mul_f32_e32 v3, v77, v73
	v_fmac_f32_e32 v97, v49, v3
	v_add_f32_e32 v3, v35, v71
	v_mul_f32_e64 v70, v3, s68
	v_exp_f32_e32 v70, v70
	v_add_f32_e32 v71, v38, v74
	v_add_f32_e32 v70, 1.0, v70
	v_mul_f32_e32 v71, 0xbfb8aa3b, v71
	v_exp_f32_e32 v71, v71
	v_rcp_f32_e32 v3, v70
	v_mul_f32_e32 v0, 0xbf60028b, v0
	v_exp_f32_e32 v70, v0
	v_add_f32_e32 v0, 1.0, v71
	v_rcp_f32_e32 v170, v0
	v_add_f32_e32 v71, v39, v75
	v_mul_f32_e32 v71, 0xbfb8aa3b, v71
	v_exp_f32_e32 v71, v71
	s_nop 0
	v_add_f32_e32 v0, 1.0, v71
	v_rcp_f32_e32 v171, v0
	v_pk_mul_f32 v[164:165], v[40:41], v[84:85]
	v_mul_f32_e32 v0, 0xbf60028b, v3
	v_pk_mul_f32 v[84:85], v[164:165], v[164:165]
	v_pk_add_f32 v[74:75], v[170:171], -1.0 op_sel_hi:[1,0]
	v_exp_f32_e32 v71, v0
	v_pk_fma_f32 v[74:75], v[46:47], v[74:75], 1.0 op_sel_hi:[1,1,0]
	v_pk_mul_f32 v[166:167], v[42:43], v[86:87]
	v_pk_mul_f32 v[74:75], v[86:87], v[74:75]
	v_pk_mul_f32 v[86:87], v[166:167], v[166:167]
	v_mul_f32_e32 v0, v78, v74
	v_fmac_f32_e32 v97, v50, v0
	v_add_f32_e32 v0, v84, v85
	v_add_f32_e32 v0, v86, v0
	v_add_f32_e32 v0, v87, v0
	v_pk_fma_f32 v[84:85], v[24:25], v[92:93], v[88:89]
	v_mul_f32_e32 v3, v79, v75
	v_add_f32_dpp v0, v0, v0 quad_perm:[1,0,3,2] row_mask:0xf bank_mask:0xf bound_ctrl:1
	v_lshlrev_b32_e32 v90, 16, v117
	v_lshlrev_b32_e32 v94, 16, v127
	v_add_f32_dpp v0, v0, v0 quad_perm:[2,3,0,1] row_mask:0xf bank_mask:0xf bound_ctrl:1
	ds_read_b128 v[80:83], v141 offset:39040
	v_fmac_f32_e32 v97, v51, v3
	v_add_f32_dpp v0, v0, v0 row_half_mirror row_mask:0xf bank_mask:0xf bound_ctrl:1
	v_sub_f32_e32 v94, v94, v90
	v_add_f32_dpp v3, v97, v97 quad_perm:[1,0,3,2] row_mask:0xf bank_mask:0xf bound_ctrl:1
	v_add_f32_dpp v0, v0, v0 row_mirror row_mask:0xf bank_mask:0xf bound_ctrl:1
	v_sqrt_f32_e32 v0, v0
	v_pk_fma_f32 v[86:87], v[26:27], v[94:95], v[90:91]
	v_xor_b32_e32 v0, 0x80000000, v0
	v_min_f32_e32 v0, 0xab8cbccc, v0
	v_rcp_f32_e32 v88, v0
	s_nop 0
	v_add_f32_dpp v0, v3, v3 quad_perm:[2,3,0,1] row_mask:0xf bank_mask:0xf bound_ctrl:1
	v_pk_mul_f32 v[90:91], v[166:167], v[88:89] op_sel_hi:[1,0]
	v_pk_mul_f32 v[88:89], v[164:165], v[88:89] op_sel_hi:[1,0]
	v_add_f32_dpp v0, v0, v0 row_half_mirror row_mask:0xf bank_mask:0xf bound_ctrl:1
	v_pk_mul_f32 v[94:95], v[170:171], v[90:91] neg_lo:[0,1] neg_hi:[0,1]
	v_pk_mul_f32 v[92:93], v[168:169], v[88:89] neg_lo:[0,1] neg_hi:[0,1]
	ds_write_b128 v156, v[68:71]
	ds_write_b128 v157, v[88:91]
	ds_write_b128 v158, v[92:95]
	ds_write_b128 v159, v[72:75]
	ds_write_b128 v160, v[76:79]
	v_add_u32_e32 v68, v150, v102
	v_mov_b32_dpp v3, v0 row_mirror row_mask:0xf bank_mask:0xf bound_ctrl:1
	ds_write_b128 v68, v[84:87]
	v_add_u32_e32 v68, v151, v102
	s_waitcnt lgkmcnt(6)
	ds_write_b128 v68, v[80:83]
	s_and_saveexec_b64 s[18:19], s[16:17]
	v_add_f32_e32 v0, v0, v3
	ds_write_b32 v145, v0
	s_or_b64 exec, exec, s[18:19]
	s_waitcnt lgkmcnt(0)
	s_waitcnt lgkmcnt(0)
	s_barrier
	s_barrier
	s_cmpk_gt_u32 s1, 0xfc
	s_cbranch_scc1 .LBB0_220
	v_add3_u32 v0, v155, s56, 48
	v_lshl_add_u64 v[60:61], s[22:23], 0, v[0:1]
	v_mov_b64_e32 v[62:63], s[94:95]
	v_mad_u64_u32 v[62:63], s[18:19], v60, s81, v[62:63]
	v_mad_i32_i24 v63, v61, s81, v63
	v_mov_b32_e32 v97, v1
	v_mov_b32_e32 v3, v1
	v_lshl_add_u64 v[60:61], v[62:63], 0, v[96:97]
	v_lshl_add_u64 v[64:65], v[62:63], 0, v[2:3]
	v_add_co_u32_e32 v62, vcc, 0xfffff000, v60
	s_nop 1
	v_addc_co_u32_e32 v63, vcc, -1, v61, vcc
	global_load_dwordx2 v[116:117], v[60:61], off offset:2048
	global_load_dwordx2 v[122:123], v[62:63], off offset:-2560
	global_load_dwordx2 v[118:119], v[60:61], off offset:1024
	global_load_dwordx2 v[120:121], v[60:61], off
	global_load_dwordx2 v[124:125], v[62:63], off offset:-1536
	global_load_dwordx2 v[126:127], v[62:63], off offset:-512
	s_nop 0
	global_load_dwordx4 v[60:63], v[64:65], off offset:3072
	s_nop 0
	global_load_dwordx4 v[64:67], v[64:65], off offset:-3584

; #define LAS __attribute__((address_space(3)))
; #define LDS_BAR() do { asm volatile("s_waitcnt lgkmcnt(0)" ::: "memory"); __builtin_amdgcn_s_barrier(); asm volatile("" ::: "memory"); } while (0)
; __device__ __forceinline__ void rwkv_block(KP p, int o, int b, int hd, LAS unsigned char* lds, const bf16_t* P, bf16_t* YB) {
;     ...
;         const int L = wid * 64 + lane, rp = L >> 3, c = L & 7;
;         f32x2 s[2][4];
; #pragma unroll
;         for (int a = 0; a < 2; ++a)
; #pragma unroll
;             for (int j = 0; j < 4; ++j) s[a][j] = (f32x2){0.f, 0.f};
;         LDS_BAR();
; #pragma unroll 1
;         for (int n = 0; n < 256; ++n) {
;             LAS float* B = (LAS float*)(lds + BUF0 + (n & 1) * BUFSZ);
;             LAS float* Wd = B; LAS float* KK = B + 1024; LAS float* BB = B + 2048; LAS float* KM = B + 3072; LAS float* Rr = B + 4096; LAS float* Vv = B + 5120; LAS float* Yy = B + 7168;
;             f32x2 sv[2][4];
; #pragma unroll
;             for (int a = 0; a < 2; ++a)
; #pragma unroll
;                 for (int j = 0; j < 4; ++j) sv[a][j] = s[a][j];
; #pragma unroll 1
;             for (int rep2 = 0; rep2 < ((DUP_MASK & 128) ? 2 : 1); ++rep2) {
;             if (rep2 == 1) {
; #pragma unroll
;                 for (int a = 0; a < 2; ++a)
; #pragma unroll
;                     for (int j = 0; j < 4; ++j) s[a][j] = sv[a][j];
;             }
; #pragma unroll
;             for (int tt = 0; tt < 16; ++tt) {
;                 const int o8 = tt * 64 + c * 8;
;                 const f32x4 ka = *(const LAS f32x4*)(KK + o8), kb = *(const LAS f32x4*)(KK + o8 + 4);
;                 const f32x4 wa = *(const LAS f32x4*)(Wd + o8), wb = *(const LAS f32x4*)(Wd + o8 + 4);
;                 const f32x4 ba = *(const LAS f32x4*)(BB + o8), bb = *(const LAS f32x4*)(BB + o8 + 4);
;                 const f32x4 ma = *(const LAS f32x4*)(KM + o8), mb = *(const LAS f32x4*)(KM + o8 + 4);
;                 const f32x4 ra = *(const LAS f32x4*)(Rr + o8), rb = *(const LAS f32x4*)(Rr + o8 + 4);
;                 const f32x2 v01 = *(const LAS f32x2*)(Vv + tt * 64 + 2 * rp);
.LBB0_232:
	s_andn2_saveexec_b64 s[10:11], s[20:21]
	s_cbranch_execz .LBB0_156
	v_and_b32_e32 v3, 7, v2
	v_and_b32_e32 v185, 15, v2
	v_lshlrev_b32_e32 v185, 3, v185
	v_add_u32_e32 v185, 0x15520, v185
	s_waitcnt lgkmcnt(0)
	s_barrier
	s_setprio 2
	v_ashrrev_i32_e32 v2, 2, v2
	v_lshlrev_b32_e32 v182, 5, v3
	v_and_b32_e32 v2, -2, v2
	v_lshlrev_b32_e32 v183, 2, v2
	v_cmp_eq_u32_e32 vcc, 0, v3
	s_mov_b64 s[12:13], exec
	s_mov_b32 s1, 0
	v_mov_b32_e32 v2, 0
	v_mov_b32_e32 v3, 0
	v_mov_b32_e32 v4, 0
	v_mov_b32_e32 v5, 0
	v_mov_b32_e32 v6, 0
	v_mov_b32_e32 v7, 0
	v_mov_b32_e32 v8, 0
	v_mov_b32_e32 v9, 0
	v_mov_b32_e32 v10, 0
	v_mov_b32_e32 v11, 0
	v_mov_b32_e32 v12, 0
	v_mov_b32_e32 v13, 0
	v_mov_b32_e32 v14, 0
	v_mov_b32_e32 v15, 0
	v_mov_b32_e32 v16, 0
	v_mov_b32_e32 v17, 0
	s_mov_b32 s7, 0xc300
	v_add_u32_e32 v180, s7, v182
	v_add_u32_e32 v181, s7, v183
	s_mov_b32 s7, 0x14340
	v_add_u32_e32 v186, s7, v182
	v_add_u32_e32 v187, s7, v183
	v_cndmask_b32_e32 v184, v185, v181, vcc
	v_cndmask_b32_e32 v188, v185, v187, vcc
	ds_read_b128 v[64:67], v180 offset:4096
	ds_read_b128 v[68:71], v180 offset:4112
	ds_read_b64 v[104:105], v181 offset:20480
	ds_read_b128 v[88:91], v180 offset:12288
	ds_read_b128 v[92:95], v180 offset:12304
	ds_read_b128 v[72:75], v180 offset:0
	ds_read_b128 v[76:79], v180 offset:16
	ds_read_b128 v[80:83], v180 offset:8192
	ds_read_b128 v[84:87], v180 offset:8208
	ds_read_b128 v[96:99], v180 offset:16384
	ds_read_b128 v[100:103], v180 offset:16400
.Lrk_scan_loop:
	s_waitcnt lgkmcnt(0)
	v_pk_mul_f32 v[20:21], v[2:3], v[64:65] op_sel_hi:[1,0]
	v_pk_mul_f32 v[22:23], v[10:11], v[68:69] op_sel_hi:[1,0]
	ds_read_b128 v[110:113], v180 offset:4352
	v_pk_fma_f32 v[20:21], v[4:5], v[64:65], v[20:21] op_sel:[0,1,0]
	v_pk_fma_f32 v[22:23], v[12:13], v[68:69], v[22:23] op_sel:[0,1,0]
	ds_read_b128 v[114:117], v180 offset:4368
	v_pk_fma_f32 v[20:21], v[6:7], v[66:67], v[20:21] op_sel_hi:[1,0,1]
	v_pk_fma_f32 v[22:23], v[14:15], v[70:71], v[22:23] op_sel_hi:[1,0,1]
	ds_read_b64 v[150:151], v181 offset:20736
	v_pk_fma_f32 v[20:21], v[8:9], v[66:67], v[20:21] op_sel:[0,1,0]
	v_pk_fma_f32 v[22:23], v[16:17], v[70:71], v[22:23] op_sel:[0,1,0]
	ds_read_b128 v[134:137], v180 offset:12544
	ds_read_b128 v[138:141], v180 offset:12560
	v_pk_add_f32 v[20:21], v[20:21], v[22:23]
	ds_read_b128 v[118:121], v180 offset:256
	ds_read_b128 v[122:125], v180 offset:272
	v_add_f32_dpp v20, v20, v20 quad_perm:[1,0,3,2] row_mask:0xf bank_mask:0xf bound_ctrl:1
	v_add_f32_dpp v21, v21, v21 quad_perm:[1,0,3,2] row_mask:0xf bank_mask:0xf bound_ctrl:1
	ds_read_b128 v[126:129], v180 offset:8448
	v_add_f32_dpp v20, v20, v20 quad_perm:[2,3,0,1] row_mask:0xf bank_mask:0xf bound_ctrl:1
	v_add_f32_dpp v21, v21, v21 quad_perm:[2,3,0,1] row_mask:0xf bank_mask:0xf bound_ctrl:1
	ds_read_b128 v[130:133], v180 offset:8464
	v_add_f32_dpp v20, v20, v20 row_half_mirror row_mask:0xf bank_mask:0xf bound_ctrl:1
	v_add_f32_dpp v21, v21, v21 row_half_mirror row_mask:0xf bank_mask:0xf bound_ctrl:1
	ds_read_b128 v[142:145], v180 offset:16640
	ds_read_b128 v[146:149], v180 offset:16656
	v_pk_mul_f32 v[24:25], v[104:105], v[88:89] op_sel_hi:[1,0]
	v_pk_mul_f32 v[26:27], v[104:105], v[88:89] op_sel:[0,1]
	v_pk_mul_f32 v[28:29], v[104:105], v[90:91] op_sel_hi:[1,0]
	v_pk_fma_f32 v[24:25], v[2:3], v[72:73], v[24:25] op_sel_hi:[1,0,1]
	v_pk_fma_f32 v[26:27], v[4:5], v[72:73], v[26:27] op_sel:[0,1,0]
	v_pk_fma_f32 v[28:29], v[6:7], v[74:75], v[28:29] op_sel_hi:[1,0,1]
	v_pk_fma_f32 v[2:3], v[20:21], v[80:81], v[24:25] op_sel_hi:[1,0,1]
	v_pk_fma_f32 v[4:5], v[20:21], v[80:81], v[26:27] op_sel:[0,1,0]
	v_pk_fma_f32 v[6:7], v[20:21], v[82:83], v[28:29] op_sel_hi:[1,0,1]
	v_pk_mul_f32 v[30:31], v[104:105], v[90:91] op_sel:[0,1]
	v_pk_mul_f32 v[32:33], v[104:105], v[92:93] op_sel_hi:[1,0]
	v_pk_mul_f32 v[34:35], v[104:105], v[92:93] op_sel:[0,1]
	v_pk_fma_f32 v[30:31], v[8:9], v[74:75], v[30:31] op_sel:[0,1,0]
	v_pk_fma_f32 v[32:33], v[10:11], v[76:77], v[32:33] op_sel_hi:[1,0,1]
	v_pk_fma_f32 v[34:35], v[12:13], v[76:77], v[34:35] op_sel:[0,1,0]
	v_pk_fma_f32 v[8:9], v[20:21], v[82:83], v[30:31] op_sel:[0,1,0]
	v_pk_fma_f32 v[10:11], v[20:21], v[84:85], v[32:33] op_sel_hi:[1,0,1]
	v_pk_fma_f32 v[12:13], v[20:21], v[84:85], v[34:35] op_sel:[0,1,0]
	v_pk_mul_f32 v[36:37], v[104:105], v[94:95] op_sel_hi:[1,0]
	v_pk_mul_f32 v[38:39], v[104:105], v[94:95] op_sel:[0,1]
	v_pk_mul_f32 v[40:41], v[2:3], v[96:97] op_sel_hi:[1,0]
	v_pk_fma_f32 v[36:37], v[14:15], v[78:79], v[36:37] op_sel_hi:[1,0,1]
	v_pk_fma_f32 v[38:39], v[16:17], v[78:79], v[38:39] op_sel:[0,1,0]
	v_pk_mul_f32 v[44:45], v[10:11], v[100:101] op_sel_hi:[1,0]
	v_pk_fma_f32 v[14:15], v[20:21], v[86:87], v[36:37] op_sel_hi:[1,0,1]
	v_pk_fma_f32 v[16:17], v[20:21], v[86:87], v[38:39] op_sel:[0,1,0]
	v_pk_fma_f32 v[40:41], v[4:5], v[96:97], v[40:41] op_sel:[0,1,0]
	v_pk_fma_f32 v[44:45], v[12:13], v[100:101], v[44:45] op_sel:[0,1,0]
	v_pk_fma_f32 v[40:41], v[6:7], v[98:99], v[40:41] op_sel_hi:[1,0,1]
	v_pk_fma_f32 v[44:45], v[14:15], v[102:103], v[44:45] op_sel_hi:[1,0,1]
	v_pk_fma_f32 v[40:41], v[8:9], v[98:99], v[40:41] op_sel:[0,1,0]
	v_pk_fma_f32 v[44:45], v[16:17], v[102:103], v[44:45] op_sel:[0,1,0]
	v_pk_add_f32 v[40:41], v[40:41], v[44:45]
	s_waitcnt lgkmcnt(0)
; __device__ __forceinline__ void rwkv_block(KP p, int o, int b, int hd, LAS unsigned char* lds, const bf16_t* P, bf16_t* YB) {
;     ...
;             for (int tt = 0; tt < 16; ++tt) {
;                 const int o8 = tt * 64 + c * 8;
;                 const f32x4 ka = *(const LAS f32x4*)(KK + o8), kb = *(const LAS f32x4*)(KK + o8 + 4);
;                 const f32x4 wa = *(const LAS f32x4*)(Wd + o8), wb = *(const LAS f32x4*)(Wd + o8 + 4);
;                 const f32x4 ba = *(const LAS f32x4*)(BB + o8), bb = *(const LAS f32x4*)(BB + o8 + 4);
;                 const f32x4 ma = *(const LAS f32x4*)(KM + o8), mb = *(const LAS f32x4*)(KM + o8 + 4);
;                 const f32x4 ra = *(const LAS f32x4*)(Rr + o8), rb = *(const LAS f32x4*)(Rr + o8 + 4);
;                 const f32x2 v01 = *(const LAS f32x2*)(Vv + tt * 64 + 2 * rp);
;                 const f32x2 k2[4] = {{ka[0], ka[1]}, {ka[2], ka[3]}, {kb[0], kb[1]}, {kb[2], kb[3]}};
;                 const f32x2 w2[4] = {{wa[0], wa[1]}, {wa[2], wa[3]}, {wb[0], wb[1]}, {wb[2], wb[3]}};
;                 const f32x2 b2[4] = {{ba[0], ba[1]}, {ba[2], ba[3]}, {bb[0], bb[1]}, {bb[2], bb[3]}};
;                 const f32x2 m2[4] = {{ma[0], ma[1]}, {ma[2], ma[3]}, {mb[0], mb[1]}, {mb[2], mb[3]}};
;                 const f32x2 r2[4] = {{ra[0], ra[1]}, {ra[2], ra[3]}, {rb[0], rb[1]}, {rb[2], rb[3]}};
;                 f32x2 accA = s[0][0] * k2[0], accB = s[1][0] * k2[0], accA2 = s[0][2] * k2[2], accB2 = s[1][2] * k2[2];
;                 accA = s[0][1] * k2[1] + accA; accB = s[1][1] * k2[1] + accB; accA2 = s[0][3] * k2[3] + accA2; accB2 = s[1][3] * k2[3] + accB2;
;                 accA = accA + accA2; accB = accB + accB2;
;                 float sa0 = accA.x + accA.y, sa1 = accB.x + accB.y;
;                 sa0 += dpp_f<0xB1>(sa0); sa1 += dpp_f<0xB1>(sa1);
;                 sa0 += dpp_f<0x4E>(sa0); sa1 += dpp_f<0x4E>(sa1);
;                 sa0 += dpp_f<0x141>(sa0); sa1 += dpp_f<0x141>(sa1);
;                 const f32x2 saA = {sa0, sa0}, saB = {sa1, sa1}, vA = {v01.x, v01.x}, vB = {v01.y, v01.y};
;                 f32x2 yA, yB;
; #pragma unroll
;                 for (int j = 0; j < 4; ++j) {
;                     f32x2 tA = vA * m2[j], tB = vB * m2[j];
;                     tA = saA * b2[j] + tA; tB = saB * b2[j] + tB;
;                     s[0][j] = s[0][j] * w2[j] + tA; s[1][j] = s[1][j] * w2[j] + tB;
	v_pk_mul_f32 v[20:21], v[2:3], v[110:111] op_sel_hi:[1,0]
	v_pk_mul_f32 v[22:23], v[10:11], v[114:115] op_sel_hi:[1,0]
	ds_read_b128 v[64:67], v180 offset:4608
	v_pk_fma_f32 v[20:21], v[4:5], v[110:111], v[20:21] op_sel:[0,1,0]
	v_pk_fma_f32 v[22:23], v[12:13], v[114:115], v[22:23] op_sel:[0,1,0]
	ds_read_b128 v[68:71], v180 offset:4624
	v_pk_fma_f32 v[20:21], v[6:7], v[112:113], v[20:21] op_sel_hi:[1,0,1]
	v_pk_fma_f32 v[22:23], v[14:15], v[116:117], v[22:23] op_sel_hi:[1,0,1]
	ds_read_b64 v[104:105], v181 offset:20992
	v_pk_fma_f32 v[20:21], v[8:9], v[112:113], v[20:21] op_sel:[0,1,0]
	v_pk_fma_f32 v[22:23], v[16:17], v[116:117], v[22:23] op_sel:[0,1,0]
	ds_read_b128 v[88:91], v180 offset:12800
	ds_read_b128 v[92:95], v180 offset:12816
	v_pk_add_f32 v[20:21], v[20:21], v[22:23]
	ds_read_b128 v[72:75], v180 offset:512
	ds_read_b128 v[76:79], v180 offset:528
	v_add_f32_dpp v20, v20, v20 quad_perm:[1,0,3,2] row_mask:0xf bank_mask:0xf bound_ctrl:1
	v_add_f32_dpp v21, v21, v21 quad_perm:[1,0,3,2] row_mask:0xf bank_mask:0xf bound_ctrl:1
	ds_read_b128 v[80:83], v180 offset:8704
	v_add_f32_dpp v20, v20, v20 quad_perm:[2,3,0,1] row_mask:0xf bank_mask:0xf bound_ctrl:1
	v_add_f32_dpp v21, v21, v21 quad_perm:[2,3,0,1] row_mask:0xf bank_mask:0xf bound_ctrl:1
	ds_read_b128 v[84:87], v180 offset:8720
	v_add_f32_dpp v20, v20, v20 row_half_mirror row_mask:0xf bank_mask:0xf bound_ctrl:1
	v_add_f32_dpp v21, v21, v21 row_half_mirror row_mask:0xf bank_mask:0xf bound_ctrl:1
	ds_read_b128 v[96:99], v180 offset:16896
	ds_read_b128 v[100:103], v180 offset:16912
	v_add_f32_dpp v40, v40, v40 quad_perm:[1,0,3,2] row_mask:0xf bank_mask:0xf bound_ctrl:1
	v_add_f32_dpp v41, v41, v41 quad_perm:[1,0,3,2] row_mask:0xf bank_mask:0xf bound_ctrl:1
	v_pk_mul_f32 v[24:25], v[150:151], v[134:135] op_sel_hi:[1,0]
	v_add_f32_dpp v40, v40, v40 quad_perm:[2,3,0,1] row_mask:0xf bank_mask:0xf bound_ctrl:1
	v_add_f32_dpp v41, v41, v41 quad_perm:[2,3,0,1] row_mask:0xf bank_mask:0xf bound_ctrl:1
	v_pk_fma_f32 v[24:25], v[2:3], v[118:119], v[24:25] op_sel_hi:[1,0,1]
	v_add_f32_dpp v40, v40, v40 row_half_mirror row_mask:0xf bank_mask:0xf bound_ctrl:1
	v_add_f32_dpp v41, v41, v41 row_half_mirror row_mask:0xf bank_mask:0xf bound_ctrl:1
	v_pk_fma_f32 v[2:3], v[20:21], v[126:127], v[24:25] op_sel_hi:[1,0,1]
	v_pk_mul_f32 v[26:27], v[150:151], v[134:135] op_sel:[0,1]
	ds_write_b64 v184, v[40:41] offset:28672
	v_pk_mul_f32 v[28:29], v[150:151], v[136:137] op_sel_hi:[1,0]
	v_pk_fma_f32 v[26:27], v[4:5], v[118:119], v[26:27] op_sel:[0,1,0]
	v_pk_mul_f32 v[30:31], v[150:151], v[136:137] op_sel:[0,1]
	v_pk_fma_f32 v[28:29], v[6:7], v[120:121], v[28:29] op_sel_hi:[1,0,1]
	v_pk_fma_f32 v[4:5], v[20:21], v[126:127], v[26:27] op_sel:[0,1,0]
	v_pk_fma_f32 v[30:31], v[8:9], v[120:121], v[30:31] op_sel:[0,1,0]
	v_pk_fma_f32 v[6:7], v[20:21], v[128:129], v[28:29] op_sel_hi:[1,0,1]
	v_pk_mul_f32 v[32:33], v[150:151], v[138:139] op_sel_hi:[1,0]
	v_pk_fma_f32 v[8:9], v[20:21], v[128:129], v[30:31] op_sel:[0,1,0]
	v_pk_mul_f32 v[34:35], v[150:151], v[138:139] op_sel:[0,1]
	v_pk_fma_f32 v[32:33], v[10:11], v[122:123], v[32:33] op_sel_hi:[1,0,1]
	v_pk_mul_f32 v[36:37], v[150:151], v[140:141] op_sel_hi:[1,0]
	v_pk_fma_f32 v[34:35], v[12:13], v[122:123], v[34:35] op_sel:[0,1,0]
	v_pk_fma_f32 v[10:11], v[20:21], v[130:131], v[32:33] op_sel_hi:[1,0,1]
	v_pk_fma_f32 v[36:37], v[14:15], v[124:125], v[36:37] op_sel_hi:[1,0,1]
	v_pk_fma_f32 v[12:13], v[20:21], v[130:131], v[34:35] op_sel:[0,1,0]
	v_pk_mul_f32 v[38:39], v[150:151], v[140:141] op_sel:[0,1]
	v_pk_fma_f32 v[14:15], v[20:21], v[132:133], v[36:37] op_sel_hi:[1,0,1]
	v_pk_mul_f32 v[42:43], v[2:3], v[142:143] op_sel_hi:[1,0]
	v_pk_fma_f32 v[38:39], v[16:17], v[124:125], v[38:39] op_sel:[0,1,0]
	v_pk_mul_f32 v[44:45], v[10:11], v[146:147] op_sel_hi:[1,0]
	v_pk_fma_f32 v[42:43], v[4:5], v[142:143], v[42:43] op_sel:[0,1,0]
	v_pk_fma_f32 v[16:17], v[20:21], v[132:133], v[38:39] op_sel:[0,1,0]
	v_pk_fma_f32 v[44:45], v[12:13], v[146:147], v[44:45] op_sel:[0,1,0]
	v_pk_fma_f32 v[42:43], v[6:7], v[144:145], v[42:43] op_sel_hi:[1,0,1]
	v_pk_fma_f32 v[44:45], v[14:15], v[148:149], v[44:45] op_sel_hi:[1,0,1]
	v_pk_fma_f32 v[42:43], v[8:9], v[144:145], v[42:43] op_sel:[0,1,0]
	v_pk_fma_f32 v[44:45], v[16:17], v[148:149], v[44:45] op_sel:[0,1,0]
	v_pk_add_f32 v[42:43], v[42:43], v[44:45]
	s_waitcnt lgkmcnt(0)
; __device__ __forceinline__ void rwkv_block(KP p, int o, int b, int hd, LAS unsigned char* lds, const bf16_t* P, bf16_t* YB) {
;     ...
;             for (int tt = 0; tt < 16; ++tt) {
;                 const int o8 = tt * 64 + c * 8;
;                 const f32x4 ka = *(const LAS f32x4*)(KK + o8), kb = *(const LAS f32x4*)(KK + o8 + 4);
;                 const f32x4 wa = *(const LAS f32x4*)(Wd + o8), wb = *(const LAS f32x4*)(Wd + o8 + 4);
;                 const f32x4 ba = *(const LAS f32x4*)(BB + o8), bb = *(const LAS f32x4*)(BB + o8 + 4);
;                 const f32x4 ma = *(const LAS f32x4*)(KM + o8), mb = *(const LAS f32x4*)(KM + o8 + 4);
;                 const f32x4 ra = *(const LAS f32x4*)(Rr + o8), rb = *(const LAS f32x4*)(Rr + o8 + 4);
;                 const f32x2 v01 = *(const LAS f32x2*)(Vv + tt * 64 + 2 * rp);
;                 const f32x2 k2[4] = {{ka[0], ka[1]}, {ka[2], ka[3]}, {kb[0], kb[1]}, {kb[2], kb[3]}};
;                 const f32x2 w2[4] = {{wa[0], wa[1]}, {wa[2], wa[3]}, {wb[0], wb[1]}, {wb[2], wb[3]}};
;                 const f32x2 b2[4] = {{ba[0], ba[1]}, {ba[2], ba[3]}, {bb[0], bb[1]}, {bb[2], bb[3]}};
;                 const f32x2 m2[4] = {{ma[0], ma[1]}, {ma[2], ma[3]}, {mb[0], mb[1]}, {mb[2], mb[3]}};
;                 const f32x2 r2[4] = {{ra[0], ra[1]}, {ra[2], ra[3]}, {rb[0], rb[1]}, {rb[2], rb[3]}};
;                 f32x2 accA = s[0][0] * k2[0], accB = s[1][0] * k2[0], accA2 = s[0][2] * k2[2], accB2 = s[1][2] * k2[2];
;                 accA = s[0][1] * k2[1] + accA; accB = s[1][1] * k2[1] + accB; accA2 = s[0][3] * k2[3] + accA2; accB2 = s[1][3] * k2[3] + accB2;
;                 accA = accA + accA2; accB = accB + accB2;
;                 float sa0 = accA.x + accA.y, sa1 = accB.x + accB.y;
;                 sa0 += dpp_f<0xB1>(sa0); sa1 += dpp_f<0xB1>(sa1);
;                 sa0 += dpp_f<0x4E>(sa0); sa1 += dpp_f<0x4E>(sa1);
;                 sa0 += dpp_f<0x141>(sa0); sa1 += dpp_f<0x141>(sa1);
;                 const f32x2 saA = {sa0, sa0}, saB = {sa1, sa1}, vA = {v01.x, v01.x}, vB = {v01.y, v01.y};
;                 f32x2 yA, yB;
; #pragma unroll
;                 for (int j = 0; j < 4; ++j) {
;                     f32x2 tA = vA * m2[j], tB = vB * m2[j];
;                     tA = saA * b2[j] + tA; tB = saB * b2[j] + tB;
;                     s[0][j] = s[0][j] * w2[j] + tA; s[1][j] = s[1][j] * w2[j] + tB;
	v_pk_mul_f32 v[20:21], v[2:3], v[64:65] op_sel_hi:[1,0]
	v_pk_mul_f32 v[22:23], v[10:11], v[68:69] op_sel_hi:[1,0]
	ds_read_b128 v[110:113], v180 offset:4864
	v_pk_fma_f32 v[20:21], v[4:5], v[64:65], v[20:21] op_sel:[0,1,0]
	v_pk_fma_f32 v[22:23], v[12:13], v[68:69], v[22:23] op_sel:[0,1,0]
	ds_read_b128 v[114:117], v180 offset:4880
	v_pk_fma_f32 v[20:21], v[6:7], v[66:67], v[20:21] op_sel_hi:[1,0,1]
	v_pk_fma_f32 v[22:23], v[14:15], v[70:71], v[22:23] op_sel_hi:[1,0,1]
	ds_read_b64 v[150:151], v181 offset:21248
	v_pk_fma_f32 v[20:21], v[8:9], v[66:67], v[20:21] op_sel:[0,1,0]
	v_pk_fma_f32 v[22:23], v[16:17], v[70:71], v[22:23] op_sel:[0,1,0]
	ds_read_b128 v[134:137], v180 offset:13056
	ds_read_b128 v[138:141], v180 offset:13072
	v_pk_add_f32 v[20:21], v[20:21], v[22:23]
	ds_read_b128 v[118:121], v180 offset:768
	ds_read_b128 v[122:125], v180 offset:784
	v_add_f32_dpp v20, v20, v20 quad_perm:[1,0,3,2] row_mask:0xf bank_mask:0xf bound_ctrl:1
	v_add_f32_dpp v21, v21, v21 quad_perm:[1,0,3,2] row_mask:0xf bank_mask:0xf bound_ctrl:1
	ds_read_b128 v[126:129], v180 offset:8960
	v_add_f32_dpp v20, v20, v20 quad_perm:[2,3,0,1] row_mask:0xf bank_mask:0xf bound_ctrl:1
	v_add_f32_dpp v21, v21, v21 quad_perm:[2,3,0,1] row_mask:0xf bank_mask:0xf bound_ctrl:1
	ds_read_b128 v[130:133], v180 offset:8976
	v_add_f32_dpp v20, v20, v20 row_half_mirror row_mask:0xf bank_mask:0xf bound_ctrl:1
	v_add_f32_dpp v21, v21, v21 row_half_mirror row_mask:0xf bank_mask:0xf bound_ctrl:1
	ds_read_b128 v[142:145], v180 offset:17152
	ds_read_b128 v[146:149], v180 offset:17168
	v_add_f32_dpp v42, v42, v42 quad_perm:[1,0,3,2] row_mask:0xf bank_mask:0xf bound_ctrl:1
	v_add_f32_dpp v43, v43, v43 quad_perm:[1,0,3,2] row_mask:0xf bank_mask:0xf bound_ctrl:1
	v_pk_mul_f32 v[24:25], v[104:105], v[88:89] op_sel_hi:[1,0]
	v_add_f32_dpp v42, v42, v42 quad_perm:[2,3,0,1] row_mask:0xf bank_mask:0xf bound_ctrl:1
	v_add_f32_dpp v43, v43, v43 quad_perm:[2,3,0,1] row_mask:0xf bank_mask:0xf bound_ctrl:1
	v_pk_fma_f32 v[24:25], v[2:3], v[72:73], v[24:25] op_sel_hi:[1,0,1]
	v_add_f32_dpp v42, v42, v42 row_half_mirror row_mask:0xf bank_mask:0xf bound_ctrl:1
	v_add_f32_dpp v43, v43, v43 row_half_mirror row_mask:0xf bank_mask:0xf bound_ctrl:1
	v_pk_fma_f32 v[2:3], v[20:21], v[80:81], v[24:25] op_sel_hi:[1,0,1]
	v_pk_mul_f32 v[26:27], v[104:105], v[88:89] op_sel:[0,1]
	ds_write_b64 v184, v[42:43] offset:28928
	v_pk_mul_f32 v[28:29], v[104:105], v[90:91] op_sel_hi:[1,0]
	v_pk_fma_f32 v[26:27], v[4:5], v[72:73], v[26:27] op_sel:[0,1,0]
	v_pk_mul_f32 v[30:31], v[104:105], v[90:91] op_sel:[0,1]
	v_pk_fma_f32 v[28:29], v[6:7], v[74:75], v[28:29] op_sel_hi:[1,0,1]
	v_pk_fma_f32 v[4:5], v[20:21], v[80:81], v[26:27] op_sel:[0,1,0]
	v_pk_fma_f32 v[30:31], v[8:9], v[74:75], v[30:31] op_sel:[0,1,0]
	v_pk_fma_f32 v[6:7], v[20:21], v[82:83], v[28:29] op_sel_hi:[1,0,1]
	v_pk_mul_f32 v[32:33], v[104:105], v[92:93] op_sel_hi:[1,0]
	v_pk_fma_f32 v[8:9], v[20:21], v[82:83], v[30:31] op_sel:[0,1,0]
	v_pk_mul_f32 v[34:35], v[104:105], v[92:93] op_sel:[0,1]
	v_pk_fma_f32 v[32:33], v[10:11], v[76:77], v[32:33] op_sel_hi:[1,0,1]
	v_pk_mul_f32 v[36:37], v[104:105], v[94:95] op_sel_hi:[1,0]
	v_pk_fma_f32 v[34:35], v[12:13], v[76:77], v[34:35] op_sel:[0,1,0]
	v_pk_fma_f32 v[10:11], v[20:21], v[84:85], v[32:33] op_sel_hi:[1,0,1]
	v_pk_fma_f32 v[36:37], v[14:15], v[78:79], v[36:37] op_sel_hi:[1,0,1]
	v_pk_fma_f32 v[12:13], v[20:21], v[84:85], v[34:35] op_sel:[0,1,0]
	v_pk_mul_f32 v[38:39], v[104:105], v[94:95] op_sel:[0,1]
	v_pk_fma_f32 v[14:15], v[20:21], v[86:87], v[36:37] op_sel_hi:[1,0,1]
	v_pk_mul_f32 v[40:41], v[2:3], v[96:97] op_sel_hi:[1,0]
	v_pk_fma_f32 v[38:39], v[16:17], v[78:79], v[38:39] op_sel:[0,1,0]
	v_pk_mul_f32 v[44:45], v[10:11], v[100:101] op_sel_hi:[1,0]
	v_pk_fma_f32 v[40:41], v[4:5], v[96:97], v[40:41] op_sel:[0,1,0]
	v_pk_fma_f32 v[16:17], v[20:21], v[86:87], v[38:39] op_sel:[0,1,0]
	v_pk_fma_f32 v[44:45], v[12:13], v[100:101], v[44:45] op_sel:[0,1,0]
	v_pk_fma_f32 v[40:41], v[6:7], v[98:99], v[40:41] op_sel_hi:[1,0,1]
	v_pk_fma_f32 v[44:45], v[14:15], v[102:103], v[44:45] op_sel_hi:[1,0,1]
	v_pk_fma_f32 v[40:41], v[8:9], v[98:99], v[40:41] op_sel:[0,1,0]
	v_pk_fma_f32 v[44:45], v[16:17], v[102:103], v[44:45] op_sel:[0,1,0]
	v_pk_add_f32 v[40:41], v[40:41], v[44:45]
	s_waitcnt lgkmcnt(0)
; __device__ __forceinline__ void rwkv_block(KP p, int o, int b, int hd, LAS unsigned char* lds, const bf16_t* P, bf16_t* YB) {
;     ...
;             for (int tt = 0; tt < 16; ++tt) {
;                 const int o8 = tt * 64 + c * 8;
;                 const f32x4 ka = *(const LAS f32x4*)(KK + o8), kb = *(const LAS f32x4*)(KK + o8 + 4);
;                 const f32x4 wa = *(const LAS f32x4*)(Wd + o8), wb = *(const LAS f32x4*)(Wd + o8 + 4);
;                 const f32x4 ba = *(const LAS f32x4*)(BB + o8), bb = *(const LAS f32x4*)(BB + o8 + 4);
;                 const f32x4 ma = *(const LAS f32x4*)(KM + o8), mb = *(const LAS f32x4*)(KM + o8 + 4);
;                 const f32x4 ra = *(const LAS f32x4*)(Rr + o8), rb = *(const LAS f32x4*)(Rr + o8 + 4);
;                 const f32x2 v01 = *(const LAS f32x2*)(Vv + tt * 64 + 2 * rp);
;                 const f32x2 k2[4] = {{ka[0], ka[1]}, {ka[2], ka[3]}, {kb[0], kb[1]}, {kb[2], kb[3]}};
;                 const f32x2 w2[4] = {{wa[0], wa[1]}, {wa[2], wa[3]}, {wb[0], wb[1]}, {wb[2], wb[3]}};
;                 const f32x2 b2[4] = {{ba[0], ba[1]}, {ba[2], ba[3]}, {bb[0], bb[1]}, {bb[2], bb[3]}};
;                 const f32x2 m2[4] = {{ma[0], ma[1]}, {ma[2], ma[3]}, {mb[0], mb[1]}, {mb[2], mb[3]}};
;                 const f32x2 r2[4] = {{ra[0], ra[1]}, {ra[2], ra[3]}, {rb[0], rb[1]}, {rb[2], rb[3]}};
;                 f32x2 accA = s[0][0] * k2[0], accB = s[1][0] * k2[0], accA2 = s[0][2] * k2[2], accB2 = s[1][2] * k2[2];
;                 accA = s[0][1] * k2[1] + accA; accB = s[1][1] * k2[1] + accB; accA2 = s[0][3] * k2[3] + accA2; accB2 = s[1][3] * k2[3] + accB2;
;                 accA = accA + accA2; accB = accB + accB2;
;                 float sa0 = accA.x + accA.y, sa1 = accB.x + accB.y;
;                 sa0 += dpp_f<0xB1>(sa0); sa1 += dpp_f<0xB1>(sa1);
;                 sa0 += dpp_f<0x4E>(sa0); sa1 += dpp_f<0x4E>(sa1);
;                 sa0 += dpp_f<0x141>(sa0); sa1 += dpp_f<0x141>(sa1);
;                 const f32x2 saA = {sa0, sa0}, saB = {sa1, sa1}, vA = {v01.x, v01.x}, vB = {v01.y, v01.y};
;                 f32x2 yA, yB;
; #pragma unroll
;                 for (int j = 0; j < 4; ++j) {
;                     f32x2 tA = vA * m2[j], tB = vB * m2[j];
;                     tA = saA * b2[j] + tA; tB = saB * b2[j] + tB;
;                     s[0][j] = s[0][j] * w2[j] + tA; s[1][j] = s[1][j] * w2[j] + tB;
	v_pk_mul_f32 v[20:21], v[2:3], v[110:111] op_sel_hi:[1,0]
	v_pk_mul_f32 v[22:23], v[10:11], v[114:115] op_sel_hi:[1,0]
	ds_read_b128 v[64:67], v180 offset:5120
	v_pk_fma_f32 v[20:21], v[4:5], v[110:111], v[20:21] op_sel:[0,1,0]
	v_pk_fma_f32 v[22:23], v[12:13], v[114:115], v[22:23] op_sel:[0,1,0]
	ds_read_b128 v[68:71], v180 offset:5136
	v_pk_fma_f32 v[20:21], v[6:7], v[112:113], v[20:21] op_sel_hi:[1,0,1]
	v_pk_fma_f32 v[22:23], v[14:15], v[116:117], v[22:23] op_sel_hi:[1,0,1]
	ds_read_b64 v[104:105], v181 offset:21504
	v_pk_fma_f32 v[20:21], v[8:9], v[112:113], v[20:21] op_sel:[0,1,0]
	v_pk_fma_f32 v[22:23], v[16:17], v[116:117], v[22:23] op_sel:[0,1,0]
	ds_read_b128 v[88:91], v180 offset:13312
	ds_read_b128 v[92:95], v180 offset:13328
	v_pk_add_f32 v[20:21], v[20:21], v[22:23]
	ds_read_b128 v[72:75], v180 offset:1024
	ds_read_b128 v[76:79], v180 offset:1040
	v_add_f32_dpp v20, v20, v20 quad_perm:[1,0,3,2] row_mask:0xf bank_mask:0xf bound_ctrl:1
	v_add_f32_dpp v21, v21, v21 quad_perm:[1,0,3,2] row_mask:0xf bank_mask:0xf bound_ctrl:1
	ds_read_b128 v[80:83], v180 offset:9216
	v_add_f32_dpp v20, v20, v20 quad_perm:[2,3,0,1] row_mask:0xf bank_mask:0xf bound_ctrl:1
	v_add_f32_dpp v21, v21, v21 quad_perm:[2,3,0,1] row_mask:0xf bank_mask:0xf bound_ctrl:1
	ds_read_b128 v[84:87], v180 offset:9232
	v_add_f32_dpp v20, v20, v20 row_half_mirror row_mask:0xf bank_mask:0xf bound_ctrl:1
	v_add_f32_dpp v21, v21, v21 row_half_mirror row_mask:0xf bank_mask:0xf bound_ctrl:1
	ds_read_b128 v[96:99], v180 offset:17408
	ds_read_b128 v[100:103], v180 offset:17424
	v_add_f32_dpp v40, v40, v40 quad_perm:[1,0,3,2] row_mask:0xf bank_mask:0xf bound_ctrl:1
	v_add_f32_dpp v41, v41, v41 quad_perm:[1,0,3,2] row_mask:0xf bank_mask:0xf bound_ctrl:1
	v_pk_mul_f32 v[24:25], v[150:151], v[134:135] op_sel_hi:[1,0]
	v_add_f32_dpp v40, v40, v40 quad_perm:[2,3,0,1] row_mask:0xf bank_mask:0xf bound_ctrl:1
	v_add_f32_dpp v41, v41, v41 quad_perm:[2,3,0,1] row_mask:0xf bank_mask:0xf bound_ctrl:1
	v_pk_fma_f32 v[24:25], v[2:3], v[118:119], v[24:25] op_sel_hi:[1,0,1]
	v_add_f32_dpp v40, v40, v40 row_half_mirror row_mask:0xf bank_mask:0xf bound_ctrl:1
	v_add_f32_dpp v41, v41, v41 row_half_mirror row_mask:0xf bank_mask:0xf bound_ctrl:1
	v_pk_fma_f32 v[2:3], v[20:21], v[126:127], v[24:25] op_sel_hi:[1,0,1]
	v_pk_mul_f32 v[26:27], v[150:151], v[134:135] op_sel:[0,1]
	ds_write_b64 v184, v[40:41] offset:29184
	v_pk_mul_f32 v[28:29], v[150:151], v[136:137] op_sel_hi:[1,0]
	v_pk_fma_f32 v[26:27], v[4:5], v[118:119], v[26:27] op_sel:[0,1,0]
	v_pk_mul_f32 v[30:31], v[150:151], v[136:137] op_sel:[0,1]
	v_pk_fma_f32 v[28:29], v[6:7], v[120:121], v[28:29] op_sel_hi:[1,0,1]
	v_pk_fma_f32 v[4:5], v[20:21], v[126:127], v[26:27] op_sel:[0,1,0]
	v_pk_fma_f32 v[30:31], v[8:9], v[120:121], v[30:31] op_sel:[0,1,0]
	v_pk_fma_f32 v[6:7], v[20:21], v[128:129], v[28:29] op_sel_hi:[1,0,1]
	v_pk_mul_f32 v[32:33], v[150:151], v[138:139] op_sel_hi:[1,0]
	v_pk_fma_f32 v[8:9], v[20:21], v[128:129], v[30:31] op_sel:[0,1,0]
	v_pk_mul_f32 v[34:35], v[150:151], v[138:139] op_sel:[0,1]
	v_pk_fma_f32 v[32:33], v[10:11], v[122:123], v[32:33] op_sel_hi:[1,0,1]
	v_pk_mul_f32 v[36:37], v[150:151], v[140:141] op_sel_hi:[1,0]
	v_pk_fma_f32 v[34:35], v[12:13], v[122:123], v[34:35] op_sel:[0,1,0]
	v_pk_fma_f32 v[10:11], v[20:21], v[130:131], v[32:33] op_sel_hi:[1,0,1]
	v_pk_fma_f32 v[36:37], v[14:15], v[124:125], v[36:37] op_sel_hi:[1,0,1]
	v_pk_fma_f32 v[12:13], v[20:21], v[130:131], v[34:35] op_sel:[0,1,0]
	v_pk_mul_f32 v[38:39], v[150:151], v[140:141] op_sel:[0,1]
	v_pk_fma_f32 v[14:15], v[20:21], v[132:133], v[36:37] op_sel_hi:[1,0,1]
	v_pk_mul_f32 v[42:43], v[2:3], v[142:143] op_sel_hi:[1,0]
	v_pk_fma_f32 v[38:39], v[16:17], v[124:125], v[38:39] op_sel:[0,1,0]
	v_pk_mul_f32 v[44:45], v[10:11], v[146:147] op_sel_hi:[1,0]
	v_pk_fma_f32 v[42:43], v[4:5], v[142:143], v[42:43] op_sel:[0,1,0]
	v_pk_fma_f32 v[16:17], v[20:21], v[132:133], v[38:39] op_sel:[0,1,0]
	v_pk_fma_f32 v[44:45], v[12:13], v[146:147], v[44:45] op_sel:[0,1,0]
	v_pk_fma_f32 v[42:43], v[6:7], v[144:145], v[42:43] op_sel_hi:[1,0,1]
	v_pk_fma_f32 v[44:45], v[14:15], v[148:149], v[44:45] op_sel_hi:[1,0,1]
	v_pk_fma_f32 v[42:43], v[8:9], v[144:145], v[42:43] op_sel:[0,1,0]
	v_pk_fma_f32 v[44:45], v[16:17], v[148:149], v[44:45] op_sel:[0,1,0]
	v_pk_add_f32 v[42:43], v[42:43], v[44:45]
	s_waitcnt lgkmcnt(0)
; __device__ __forceinline__ void rwkv_block(KP p, int o, int b, int hd, LAS unsigned char* lds, const bf16_t* P, bf16_t* YB) {
;     ...
;             for (int tt = 0; tt < 16; ++tt) {
;                 const int o8 = tt * 64 + c * 8;
;                 const f32x4 ka = *(const LAS f32x4*)(KK + o8), kb = *(const LAS f32x4*)(KK + o8 + 4);
;                 const f32x4 wa = *(const LAS f32x4*)(Wd + o8), wb = *(const LAS f32x4*)(Wd + o8 + 4);
;                 const f32x4 ba = *(const LAS f32x4*)(BB + o8), bb = *(const LAS f32x4*)(BB + o8 + 4);
;                 const f32x4 ma = *(const LAS f32x4*)(KM + o8), mb = *(const LAS f32x4*)(KM + o8 + 4);
;                 const f32x4 ra = *(const LAS f32x4*)(Rr + o8), rb = *(const LAS f32x4*)(Rr + o8 + 4);
;                 const f32x2 v01 = *(const LAS f32x2*)(Vv + tt * 64 + 2 * rp);
;                 const f32x2 k2[4] = {{ka[0], ka[1]}, {ka[2], ka[3]}, {kb[0], kb[1]}, {kb[2], kb[3]}};
;                 const f32x2 w2[4] = {{wa[0], wa[1]}, {wa[2], wa[3]}, {wb[0], wb[1]}, {wb[2], wb[3]}};
;                 const f32x2 b2[4] = {{ba[0], ba[1]}, {ba[2], ba[3]}, {bb[0], bb[1]}, {bb[2], bb[3]}};
;                 const f32x2 m2[4] = {{ma[0], ma[1]}, {ma[2], ma[3]}, {mb[0], mb[1]}, {mb[2], mb[3]}};
;                 const f32x2 r2[4] = {{ra[0], ra[1]}, {ra[2], ra[3]}, {rb[0], rb[1]}, {rb[2], rb[3]}};
;                 f32x2 accA = s[0][0] * k2[0], accB = s[1][0] * k2[0], accA2 = s[0][2] * k2[2], accB2 = s[1][2] * k2[2];
;                 accA = s[0][1] * k2[1] + accA; accB = s[1][1] * k2[1] + accB; accA2 = s[0][3] * k2[3] + accA2; accB2 = s[1][3] * k2[3] + accB2;
;                 accA = accA + accA2; accB = accB + accB2;
;                 float sa0 = accA.x + accA.y, sa1 = accB.x + accB.y;
;                 sa0 += dpp_f<0xB1>(sa0); sa1 += dpp_f<0xB1>(sa1);
;                 sa0 += dpp_f<0x4E>(sa0); sa1 += dpp_f<0x4E>(sa1);
;                 sa0 += dpp_f<0x141>(sa0); sa1 += dpp_f<0x141>(sa1);
;                 const f32x2 saA = {sa0, sa0}, saB = {sa1, sa1}, vA = {v01.x, v01.x}, vB = {v01.y, v01.y};
;                 f32x2 yA, yB;
; #pragma unroll
;                 for (int j = 0; j < 4; ++j) {
;                     f32x2 tA = vA * m2[j], tB = vB * m2[j];
;                     tA = saA * b2[j] + tA; tB = saB * b2[j] + tB;
;                     s[0][j] = s[0][j] * w2[j] + tA; s[1][j] = s[1][j] * w2[j] + tB;
	v_pk_mul_f32 v[20:21], v[2:3], v[64:65] op_sel_hi:[1,0]
	v_pk_mul_f32 v[22:23], v[10:11], v[68:69] op_sel_hi:[1,0]
	ds_read_b128 v[110:113], v180 offset:5376
	v_pk_fma_f32 v[20:21], v[4:5], v[64:65], v[20:21] op_sel:[0,1,0]
	v_pk_fma_f32 v[22:23], v[12:13], v[68:69], v[22:23] op_sel:[0,1,0]
	ds_read_b128 v[114:117], v180 offset:5392
	v_pk_fma_f32 v[20:21], v[6:7], v[66:67], v[20:21] op_sel_hi:[1,0,1]
	v_pk_fma_f32 v[22:23], v[14:15], v[70:71], v[22:23] op_sel_hi:[1,0,1]
	ds_read_b64 v[150:151], v181 offset:21760
	v_pk_fma_f32 v[20:21], v[8:9], v[66:67], v[20:21] op_sel:[0,1,0]
	v_pk_fma_f32 v[22:23], v[16:17], v[70:71], v[22:23] op_sel:[0,1,0]
	ds_read_b128 v[134:137], v180 offset:13568
	ds_read_b128 v[138:141], v180 offset:13584
	v_pk_add_f32 v[20:21], v[20:21], v[22:23]
	ds_read_b128 v[118:121], v180 offset:1280
	ds_read_b128 v[122:125], v180 offset:1296
	v_add_f32_dpp v20, v20, v20 quad_perm:[1,0,3,2] row_mask:0xf bank_mask:0xf bound_ctrl:1
	v_add_f32_dpp v21, v21, v21 quad_perm:[1,0,3,2] row_mask:0xf bank_mask:0xf bound_ctrl:1
	ds_read_b128 v[126:129], v180 offset:9472
	v_add_f32_dpp v20, v20, v20 quad_perm:[2,3,0,1] row_mask:0xf bank_mask:0xf bound_ctrl:1
	v_add_f32_dpp v21, v21, v21 quad_perm:[2,3,0,1] row_mask:0xf bank_mask:0xf bound_ctrl:1
	ds_read_b128 v[130:133], v180 offset:9488
	v_add_f32_dpp v20, v20, v20 row_half_mirror row_mask:0xf bank_mask:0xf bound_ctrl:1
	v_add_f32_dpp v21, v21, v21 row_half_mirror row_mask:0xf bank_mask:0xf bound_ctrl:1
	ds_read_b128 v[142:145], v180 offset:17664
	ds_read_b128 v[146:149], v180 offset:17680
	v_add_f32_dpp v42, v42, v42 quad_perm:[1,0,3,2] row_mask:0xf bank_mask:0xf bound_ctrl:1
	v_add_f32_dpp v43, v43, v43 quad_perm:[1,0,3,2] row_mask:0xf bank_mask:0xf bound_ctrl:1
	v_pk_mul_f32 v[24:25], v[104:105], v[88:89] op_sel_hi:[1,0]
	v_add_f32_dpp v42, v42, v42 quad_perm:[2,3,0,1] row_mask:0xf bank_mask:0xf bound_ctrl:1
	v_add_f32_dpp v43, v43, v43 quad_perm:[2,3,0,1] row_mask:0xf bank_mask:0xf bound_ctrl:1
	v_pk_fma_f32 v[24:25], v[2:3], v[72:73], v[24:25] op_sel_hi:[1,0,1]
	v_add_f32_dpp v42, v42, v42 row_half_mirror row_mask:0xf bank_mask:0xf bound_ctrl:1
	v_add_f32_dpp v43, v43, v43 row_half_mirror row_mask:0xf bank_mask:0xf bound_ctrl:1
	v_pk_fma_f32 v[2:3], v[20:21], v[80:81], v[24:25] op_sel_hi:[1,0,1]
	v_pk_mul_f32 v[26:27], v[104:105], v[88:89] op_sel:[0,1]
	ds_write_b64 v184, v[42:43] offset:29440
	v_pk_mul_f32 v[28:29], v[104:105], v[90:91] op_sel_hi:[1,0]
	v_pk_fma_f32 v[26:27], v[4:5], v[72:73], v[26:27] op_sel:[0,1,0]
	v_pk_mul_f32 v[30:31], v[104:105], v[90:91] op_sel:[0,1]
	v_pk_fma_f32 v[28:29], v[6:7], v[74:75], v[28:29] op_sel_hi:[1,0,1]
	v_pk_fma_f32 v[4:5], v[20:21], v[80:81], v[26:27] op_sel:[0,1,0]
	v_pk_fma_f32 v[30:31], v[8:9], v[74:75], v[30:31] op_sel:[0,1,0]
	v_pk_fma_f32 v[6:7], v[20:21], v[82:83], v[28:29] op_sel_hi:[1,0,1]
	v_pk_mul_f32 v[32:33], v[104:105], v[92:93] op_sel_hi:[1,0]
	v_pk_fma_f32 v[8:9], v[20:21], v[82:83], v[30:31] op_sel:[0,1,0]
	v_pk_mul_f32 v[34:35], v[104:105], v[92:93] op_sel:[0,1]
	v_pk_fma_f32 v[32:33], v[10:11], v[76:77], v[32:33] op_sel_hi:[1,0,1]
	v_pk_mul_f32 v[36:37], v[104:105], v[94:95] op_sel_hi:[1,0]
	v_pk_fma_f32 v[34:35], v[12:13], v[76:77], v[34:35] op_sel:[0,1,0]
	v_pk_fma_f32 v[10:11], v[20:21], v[84:85], v[32:33] op_sel_hi:[1,0,1]
	v_pk_fma_f32 v[36:37], v[14:15], v[78:79], v[36:37] op_sel_hi:[1,0,1]
	v_pk_fma_f32 v[12:13], v[20:21], v[84:85], v[34:35] op_sel:[0,1,0]
	v_pk_mul_f32 v[38:39], v[104:105], v[94:95] op_sel:[0,1]
	v_pk_fma_f32 v[14:15], v[20:21], v[86:87], v[36:37] op_sel_hi:[1,0,1]
	v_pk_mul_f32 v[40:41], v[2:3], v[96:97] op_sel_hi:[1,0]
	v_pk_fma_f32 v[38:39], v[16:17], v[78:79], v[38:39] op_sel:[0,1,0]
	v_pk_mul_f32 v[44:45], v[10:11], v[100:101] op_sel_hi:[1,0]
	v_pk_fma_f32 v[40:41], v[4:5], v[96:97], v[40:41] op_sel:[0,1,0]
	v_pk_fma_f32 v[16:17], v[20:21], v[86:87], v[38:39] op_sel:[0,1,0]
	v_pk_fma_f32 v[44:45], v[12:13], v[100:101], v[44:45] op_sel:[0,1,0]
	v_pk_fma_f32 v[40:41], v[6:7], v[98:99], v[40:41] op_sel_hi:[1,0,1]
	v_pk_fma_f32 v[44:45], v[14:15], v[102:103], v[44:45] op_sel_hi:[1,0,1]
	v_pk_fma_f32 v[40:41], v[8:9], v[98:99], v[40:41] op_sel:[0,1,0]
	v_pk_fma_f32 v[44:45], v[16:17], v[102:103], v[44:45] op_sel:[0,1,0]
	v_pk_add_f32 v[40:41], v[40:41], v[44:45]
	s_waitcnt lgkmcnt(0)
; __device__ __forceinline__ void rwkv_block(KP p, int o, int b, int hd, LAS unsigned char* lds, const bf16_t* P, bf16_t* YB) {
;     ...
;             for (int tt = 0; tt < 16; ++tt) {
;                 const int o8 = tt * 64 + c * 8;
;                 const f32x4 ka = *(const LAS f32x4*)(KK + o8), kb = *(const LAS f32x4*)(KK + o8 + 4);
;                 const f32x4 wa = *(const LAS f32x4*)(Wd + o8), wb = *(const LAS f32x4*)(Wd + o8 + 4);
;                 const f32x4 ba = *(const LAS f32x4*)(BB + o8), bb = *(const LAS f32x4*)(BB + o8 + 4);
;                 const f32x4 ma = *(const LAS f32x4*)(KM + o8), mb = *(const LAS f32x4*)(KM + o8 + 4);
;                 const f32x4 ra = *(const LAS f32x4*)(Rr + o8), rb = *(const LAS f32x4*)(Rr + o8 + 4);
;                 const f32x2 v01 = *(const LAS f32x2*)(Vv + tt * 64 + 2 * rp);
;                 const f32x2 k2[4] = {{ka[0], ka[1]}, {ka[2], ka[3]}, {kb[0], kb[1]}, {kb[2], kb[3]}};
;                 const f32x2 w2[4] = {{wa[0], wa[1]}, {wa[2], wa[3]}, {wb[0], wb[1]}, {wb[2], wb[3]}};
;                 const f32x2 b2[4] = {{ba[0], ba[1]}, {ba[2], ba[3]}, {bb[0], bb[1]}, {bb[2], bb[3]}};
;                 const f32x2 m2[4] = {{ma[0], ma[1]}, {ma[2], ma[3]}, {mb[0], mb[1]}, {mb[2], mb[3]}};
;                 const f32x2 r2[4] = {{ra[0], ra[1]}, {ra[2], ra[3]}, {rb[0], rb[1]}, {rb[2], rb[3]}};
;                 f32x2 accA = s[0][0] * k2[0], accB = s[1][0] * k2[0], accA2 = s[0][2] * k2[2], accB2 = s[1][2] * k2[2];
;                 accA = s[0][1] * k2[1] + accA; accB = s[1][1] * k2[1] + accB; accA2 = s[0][3] * k2[3] + accA2; accB2 = s[1][3] * k2[3] + accB2;
;                 accA = accA + accA2; accB = accB + accB2;
;                 float sa0 = accA.x + accA.y, sa1 = accB.x + accB.y;
;                 sa0 += dpp_f<0xB1>(sa0); sa1 += dpp_f<0xB1>(sa1);
;                 sa0 += dpp_f<0x4E>(sa0); sa1 += dpp_f<0x4E>(sa1);
;                 sa0 += dpp_f<0x141>(sa0); sa1 += dpp_f<0x141>(sa1);
;                 const f32x2 saA = {sa0, sa0}, saB = {sa1, sa1}, vA = {v01.x, v01.x}, vB = {v01.y, v01.y};
;                 f32x2 yA, yB;
; #pragma unroll
;                 for (int j = 0; j < 4; ++j) {
;                     f32x2 tA = vA * m2[j], tB = vB * m2[j];
;                     tA = saA * b2[j] + tA; tB = saB * b2[j] + tB;
;                     s[0][j] = s[0][j] * w2[j] + tA; s[1][j] = s[1][j] * w2[j] + tB;
	v_pk_mul_f32 v[20:21], v[2:3], v[110:111] op_sel_hi:[1,0]
	v_pk_mul_f32 v[22:23], v[10:11], v[114:115] op_sel_hi:[1,0]
	ds_read_b128 v[64:67], v180 offset:5632
	v_pk_fma_f32 v[20:21], v[4:5], v[110:111], v[20:21] op_sel:[0,1,0]
	v_pk_fma_f32 v[22:23], v[12:13], v[114:115], v[22:23] op_sel:[0,1,0]
	ds_read_b128 v[68:71], v180 offset:5648
	v_pk_fma_f32 v[20:21], v[6:7], v[112:113], v[20:21] op_sel_hi:[1,0,1]
	v_pk_fma_f32 v[22:23], v[14:15], v[116:117], v[22:23] op_sel_hi:[1,0,1]
	ds_read_b64 v[104:105], v181 offset:22016
	v_pk_fma_f32 v[20:21], v[8:9], v[112:113], v[20:21] op_sel:[0,1,0]
	v_pk_fma_f32 v[22:23], v[16:17], v[116:117], v[22:23] op_sel:[0,1,0]
	ds_read_b128 v[88:91], v180 offset:13824
	ds_read_b128 v[92:95], v180 offset:13840
	v_pk_add_f32 v[20:21], v[20:21], v[22:23]
	ds_read_b128 v[72:75], v180 offset:1536
	ds_read_b128 v[76:79], v180 offset:1552
	v_add_f32_dpp v20, v20, v20 quad_perm:[1,0,3,2] row_mask:0xf bank_mask:0xf bound_ctrl:1
	v_add_f32_dpp v21, v21, v21 quad_perm:[1,0,3,2] row_mask:0xf bank_mask:0xf bound_ctrl:1
	ds_read_b128 v[80:83], v180 offset:9728
	v_add_f32_dpp v20, v20, v20 quad_perm:[2,3,0,1] row_mask:0xf bank_mask:0xf bound_ctrl:1
	v_add_f32_dpp v21, v21, v21 quad_perm:[2,3,0,1] row_mask:0xf bank_mask:0xf bound_ctrl:1
	ds_read_b128 v[84:87], v180 offset:9744
	v_add_f32_dpp v20, v20, v20 row_half_mirror row_mask:0xf bank_mask:0xf bound_ctrl:1
	v_add_f32_dpp v21, v21, v21 row_half_mirror row_mask:0xf bank_mask:0xf bound_ctrl:1
	ds_read_b128 v[96:99], v180 offset:17920
	ds_read_b128 v[100:103], v180 offset:17936
	v_add_f32_dpp v40, v40, v40 quad_perm:[1,0,3,2] row_mask:0xf bank_mask:0xf bound_ctrl:1
	v_add_f32_dpp v41, v41, v41 quad_perm:[1,0,3,2] row_mask:0xf bank_mask:0xf bound_ctrl:1
	v_pk_mul_f32 v[24:25], v[150:151], v[134:135] op_sel_hi:[1,0]
	v_add_f32_dpp v40, v40, v40 quad_perm:[2,3,0,1] row_mask:0xf bank_mask:0xf bound_ctrl:1
	v_add_f32_dpp v41, v41, v41 quad_perm:[2,3,0,1] row_mask:0xf bank_mask:0xf bound_ctrl:1
	v_pk_fma_f32 v[24:25], v[2:3], v[118:119], v[24:25] op_sel_hi:[1,0,1]
	v_add_f32_dpp v40, v40, v40 row_half_mirror row_mask:0xf bank_mask:0xf bound_ctrl:1
	v_add_f32_dpp v41, v41, v41 row_half_mirror row_mask:0xf bank_mask:0xf bound_ctrl:1
	v_pk_fma_f32 v[2:3], v[20:21], v[126:127], v[24:25] op_sel_hi:[1,0,1]
	v_pk_mul_f32 v[26:27], v[150:151], v[134:135] op_sel:[0,1]
	ds_write_b64 v184, v[40:41] offset:29696
	v_pk_mul_f32 v[28:29], v[150:151], v[136:137] op_sel_hi:[1,0]
	v_pk_fma_f32 v[26:27], v[4:5], v[118:119], v[26:27] op_sel:[0,1,0]
	v_pk_mul_f32 v[30:31], v[150:151], v[136:137] op_sel:[0,1]
	v_pk_fma_f32 v[28:29], v[6:7], v[120:121], v[28:29] op_sel_hi:[1,0,1]
	v_pk_fma_f32 v[4:5], v[20:21], v[126:127], v[26:27] op_sel:[0,1,0]
	v_pk_fma_f32 v[30:31], v[8:9], v[120:121], v[30:31] op_sel:[0,1,0]
	v_pk_fma_f32 v[6:7], v[20:21], v[128:129], v[28:29] op_sel_hi:[1,0,1]
	v_pk_mul_f32 v[32:33], v[150:151], v[138:139] op_sel_hi:[1,0]
	v_pk_fma_f32 v[8:9], v[20:21], v[128:129], v[30:31] op_sel:[0,1,0]
	v_pk_mul_f32 v[34:35], v[150:151], v[138:139] op_sel:[0,1]
	v_pk_fma_f32 v[32:33], v[10:11], v[122:123], v[32:33] op_sel_hi:[1,0,1]
	v_pk_mul_f32 v[36:37], v[150:151], v[140:141] op_sel_hi:[1,0]
	v_pk_fma_f32 v[34:35], v[12:13], v[122:123], v[34:35] op_sel:[0,1,0]
	v_pk_fma_f32 v[10:11], v[20:21], v[130:131], v[32:33] op_sel_hi:[1,0,1]
	v_pk_fma_f32 v[36:37], v[14:15], v[124:125], v[36:37] op_sel_hi:[1,0,1]
	v_pk_fma_f32 v[12:13], v[20:21], v[130:131], v[34:35] op_sel:[0,1,0]
	v_pk_mul_f32 v[38:39], v[150:151], v[140:141] op_sel:[0,1]
	v_pk_fma_f32 v[14:15], v[20:21], v[132:133], v[36:37] op_sel_hi:[1,0,1]
	v_pk_mul_f32 v[42:43], v[2:3], v[142:143] op_sel_hi:[1,0]
	v_pk_fma_f32 v[38:39], v[16:17], v[124:125], v[38:39] op_sel:[0,1,0]
	v_pk_mul_f32 v[44:45], v[10:11], v[146:147] op_sel_hi:[1,0]
	v_pk_fma_f32 v[42:43], v[4:5], v[142:143], v[42:43] op_sel:[0,1,0]
	v_pk_fma_f32 v[16:17], v[20:21], v[132:133], v[38:39] op_sel:[0,1,0]
	v_pk_fma_f32 v[44:45], v[12:13], v[146:147], v[44:45] op_sel:[0,1,0]
	v_pk_fma_f32 v[42:43], v[6:7], v[144:145], v[42:43] op_sel_hi:[1,0,1]
	v_pk_fma_f32 v[44:45], v[14:15], v[148:149], v[44:45] op_sel_hi:[1,0,1]
	v_pk_fma_f32 v[42:43], v[8:9], v[144:145], v[42:43] op_sel:[0,1,0]
	v_pk_fma_f32 v[44:45], v[16:17], v[148:149], v[44:45] op_sel:[0,1,0]
	v_pk_add_f32 v[42:43], v[42:43], v[44:45]
	s_waitcnt lgkmcnt(0)
; __device__ __forceinline__ void rwkv_block(KP p, int o, int b, int hd, LAS unsigned char* lds, const bf16_t* P, bf16_t* YB) {
;     ...
;             for (int tt = 0; tt < 16; ++tt) {
;                 const int o8 = tt * 64 + c * 8;
;                 const f32x4 ka = *(const LAS f32x4*)(KK + o8), kb = *(const LAS f32x4*)(KK + o8 + 4);
;                 const f32x4 wa = *(const LAS f32x4*)(Wd + o8), wb = *(const LAS f32x4*)(Wd + o8 + 4);
;                 const f32x4 ba = *(const LAS f32x4*)(BB + o8), bb = *(const LAS f32x4*)(BB + o8 + 4);
;                 const f32x4 ma = *(const LAS f32x4*)(KM + o8), mb = *(const LAS f32x4*)(KM + o8 + 4);
;                 const f32x4 ra = *(const LAS f32x4*)(Rr + o8), rb = *(const LAS f32x4*)(Rr + o8 + 4);
;                 const f32x2 v01 = *(const LAS f32x2*)(Vv + tt * 64 + 2 * rp);
;                 const f32x2 k2[4] = {{ka[0], ka[1]}, {ka[2], ka[3]}, {kb[0], kb[1]}, {kb[2], kb[3]}};
;                 const f32x2 w2[4] = {{wa[0], wa[1]}, {wa[2], wa[3]}, {wb[0], wb[1]}, {wb[2], wb[3]}};
;                 const f32x2 b2[4] = {{ba[0], ba[1]}, {ba[2], ba[3]}, {bb[0], bb[1]}, {bb[2], bb[3]}};
;                 const f32x2 m2[4] = {{ma[0], ma[1]}, {ma[2], ma[3]}, {mb[0], mb[1]}, {mb[2], mb[3]}};
;                 const f32x2 r2[4] = {{ra[0], ra[1]}, {ra[2], ra[3]}, {rb[0], rb[1]}, {rb[2], rb[3]}};
;                 f32x2 accA = s[0][0] * k2[0], accB = s[1][0] * k2[0], accA2 = s[0][2] * k2[2], accB2 = s[1][2] * k2[2];
;                 accA = s[0][1] * k2[1] + accA; accB = s[1][1] * k2[1] + accB; accA2 = s[0][3] * k2[3] + accA2; accB2 = s[1][3] * k2[3] + accB2;
;                 accA = accA + accA2; accB = accB + accB2;
;                 float sa0 = accA.x + accA.y, sa1 = accB.x + accB.y;
;                 sa0 += dpp_f<0xB1>(sa0); sa1 += dpp_f<0xB1>(sa1);
;                 sa0 += dpp_f<0x4E>(sa0); sa1 += dpp_f<0x4E>(sa1);
;                 sa0 += dpp_f<0x141>(sa0); sa1 += dpp_f<0x141>(sa1);
;                 const f32x2 saA = {sa0, sa0}, saB = {sa1, sa1}, vA = {v01.x, v01.x}, vB = {v01.y, v01.y};
;                 f32x2 yA, yB;
; #pragma unroll
;                 for (int j = 0; j < 4; ++j) {
;                     f32x2 tA = vA * m2[j], tB = vB * m2[j];
;                     tA = saA * b2[j] + tA; tB = saB * b2[j] + tB;
;                     s[0][j] = s[0][j] * w2[j] + tA; s[1][j] = s[1][j] * w2[j] + tB;
	v_pk_mul_f32 v[20:21], v[2:3], v[64:65] op_sel_hi:[1,0]
	v_pk_mul_f32 v[22:23], v[10:11], v[68:69] op_sel_hi:[1,0]
	ds_read_b128 v[110:113], v180 offset:5888
	v_pk_fma_f32 v[20:21], v[4:5], v[64:65], v[20:21] op_sel:[0,1,0]
	v_pk_fma_f32 v[22:23], v[12:13], v[68:69], v[22:23] op_sel:[0,1,0]
	ds_read_b128 v[114:117], v180 offset:5904
	v_pk_fma_f32 v[20:21], v[6:7], v[66:67], v[20:21] op_sel_hi:[1,0,1]
	v_pk_fma_f32 v[22:23], v[14:15], v[70:71], v[22:23] op_sel_hi:[1,0,1]
	ds_read_b64 v[150:151], v181 offset:22272
	v_pk_fma_f32 v[20:21], v[8:9], v[66:67], v[20:21] op_sel:[0,1,0]
	v_pk_fma_f32 v[22:23], v[16:17], v[70:71], v[22:23] op_sel:[0,1,0]
	ds_read_b128 v[134:137], v180 offset:14080
	ds_read_b128 v[138:141], v180 offset:14096
	v_pk_add_f32 v[20:21], v[20:21], v[22:23]
	ds_read_b128 v[118:121], v180 offset:1792
	ds_read_b128 v[122:125], v180 offset:1808
	v_add_f32_dpp v20, v20, v20 quad_perm:[1,0,3,2] row_mask:0xf bank_mask:0xf bound_ctrl:1
	v_add_f32_dpp v21, v21, v21 quad_perm:[1,0,3,2] row_mask:0xf bank_mask:0xf bound_ctrl:1
	ds_read_b128 v[126:129], v180 offset:9984
	v_add_f32_dpp v20, v20, v20 quad_perm:[2,3,0,1] row_mask:0xf bank_mask:0xf bound_ctrl:1
	v_add_f32_dpp v21, v21, v21 quad_perm:[2,3,0,1] row_mask:0xf bank_mask:0xf bound_ctrl:1
	ds_read_b128 v[130:133], v180 offset:10000
	v_add_f32_dpp v20, v20, v20 row_half_mirror row_mask:0xf bank_mask:0xf bound_ctrl:1
	v_add_f32_dpp v21, v21, v21 row_half_mirror row_mask:0xf bank_mask:0xf bound_ctrl:1
	ds_read_b128 v[142:145], v180 offset:18176
	ds_read_b128 v[146:149], v180 offset:18192
	v_add_f32_dpp v42, v42, v42 quad_perm:[1,0,3,2] row_mask:0xf bank_mask:0xf bound_ctrl:1
	v_add_f32_dpp v43, v43, v43 quad_perm:[1,0,3,2] row_mask:0xf bank_mask:0xf bound_ctrl:1
	v_pk_mul_f32 v[24:25], v[104:105], v[88:89] op_sel_hi:[1,0]
	v_add_f32_dpp v42, v42, v42 quad_perm:[2,3,0,1] row_mask:0xf bank_mask:0xf bound_ctrl:1
	v_add_f32_dpp v43, v43, v43 quad_perm:[2,3,0,1] row_mask:0xf bank_mask:0xf bound_ctrl:1
	v_pk_fma_f32 v[24:25], v[2:3], v[72:73], v[24:25] op_sel_hi:[1,0,1]
	v_add_f32_dpp v42, v42, v42 row_half_mirror row_mask:0xf bank_mask:0xf bound_ctrl:1
	v_add_f32_dpp v43, v43, v43 row_half_mirror row_mask:0xf bank_mask:0xf bound_ctrl:1
	v_pk_fma_f32 v[2:3], v[20:21], v[80:81], v[24:25] op_sel_hi:[1,0,1]
	v_pk_mul_f32 v[26:27], v[104:105], v[88:89] op_sel:[0,1]
	ds_write_b64 v184, v[42:43] offset:29952
	v_pk_mul_f32 v[28:29], v[104:105], v[90:91] op_sel_hi:[1,0]
	v_pk_fma_f32 v[26:27], v[4:5], v[72:73], v[26:27] op_sel:[0,1,0]
	v_pk_mul_f32 v[30:31], v[104:105], v[90:91] op_sel:[0,1]
	v_pk_fma_f32 v[28:29], v[6:7], v[74:75], v[28:29] op_sel_hi:[1,0,1]
	v_pk_fma_f32 v[4:5], v[20:21], v[80:81], v[26:27] op_sel:[0,1,0]
	v_pk_fma_f32 v[30:31], v[8:9], v[74:75], v[30:31] op_sel:[0,1,0]
	v_pk_fma_f32 v[6:7], v[20:21], v[82:83], v[28:29] op_sel_hi:[1,0,1]
	v_pk_mul_f32 v[32:33], v[104:105], v[92:93] op_sel_hi:[1,0]
	v_pk_fma_f32 v[8:9], v[20:21], v[82:83], v[30:31] op_sel:[0,1,0]
	v_pk_mul_f32 v[34:35], v[104:105], v[92:93] op_sel:[0,1]
	v_pk_fma_f32 v[32:33], v[10:11], v[76:77], v[32:33] op_sel_hi:[1,0,1]
	v_pk_mul_f32 v[36:37], v[104:105], v[94:95] op_sel_hi:[1,0]
	v_pk_fma_f32 v[34:35], v[12:13], v[76:77], v[34:35] op_sel:[0,1,0]
	v_pk_fma_f32 v[10:11], v[20:21], v[84:85], v[32:33] op_sel_hi:[1,0,1]
	v_pk_fma_f32 v[36:37], v[14:15], v[78:79], v[36:37] op_sel_hi:[1,0,1]
	v_pk_fma_f32 v[12:13], v[20:21], v[84:85], v[34:35] op_sel:[0,1,0]
	v_pk_mul_f32 v[38:39], v[104:105], v[94:95] op_sel:[0,1]
	v_pk_fma_f32 v[14:15], v[20:21], v[86:87], v[36:37] op_sel_hi:[1,0,1]
	v_pk_mul_f32 v[40:41], v[2:3], v[96:97] op_sel_hi:[1,0]
	v_pk_fma_f32 v[38:39], v[16:17], v[78:79], v[38:39] op_sel:[0,1,0]
	v_pk_mul_f32 v[44:45], v[10:11], v[100:101] op_sel_hi:[1,0]
	v_pk_fma_f32 v[40:41], v[4:5], v[96:97], v[40:41] op_sel:[0,1,0]
	v_pk_fma_f32 v[16:17], v[20:21], v[86:87], v[38:39] op_sel:[0,1,0]
	v_pk_fma_f32 v[44:45], v[12:13], v[100:101], v[44:45] op_sel:[0,1,0]
	v_pk_fma_f32 v[40:41], v[6:7], v[98:99], v[40:41] op_sel_hi:[1,0,1]
	v_pk_fma_f32 v[44:45], v[14:15], v[102:103], v[44:45] op_sel_hi:[1,0,1]
	v_pk_fma_f32 v[40:41], v[8:9], v[98:99], v[40:41] op_sel:[0,1,0]
	v_pk_fma_f32 v[44:45], v[16:17], v[102:103], v[44:45] op_sel:[0,1,0]
	v_pk_add_f32 v[40:41], v[40:41], v[44:45]
	s_waitcnt lgkmcnt(0)
; __device__ __forceinline__ void rwkv_block(KP p, int o, int b, int hd, LAS unsigned char* lds, const bf16_t* P, bf16_t* YB) {
;     ...
;             for (int tt = 0; tt < 16; ++tt) {
;                 const int o8 = tt * 64 + c * 8;
;                 const f32x4 ka = *(const LAS f32x4*)(KK + o8), kb = *(const LAS f32x4*)(KK + o8 + 4);
;                 const f32x4 wa = *(const LAS f32x4*)(Wd + o8), wb = *(const LAS f32x4*)(Wd + o8 + 4);
;                 const f32x4 ba = *(const LAS f32x4*)(BB + o8), bb = *(const LAS f32x4*)(BB + o8 + 4);
;                 const f32x4 ma = *(const LAS f32x4*)(KM + o8), mb = *(const LAS f32x4*)(KM + o8 + 4);
;                 const f32x4 ra = *(const LAS f32x4*)(Rr + o8), rb = *(const LAS f32x4*)(Rr + o8 + 4);
;                 const f32x2 v01 = *(const LAS f32x2*)(Vv + tt * 64 + 2 * rp);
;                 const f32x2 k2[4] = {{ka[0], ka[1]}, {ka[2], ka[3]}, {kb[0], kb[1]}, {kb[2], kb[3]}};
;                 const f32x2 w2[4] = {{wa[0], wa[1]}, {wa[2], wa[3]}, {wb[0], wb[1]}, {wb[2], wb[3]}};
;                 const f32x2 b2[4] = {{ba[0], ba[1]}, {ba[2], ba[3]}, {bb[0], bb[1]}, {bb[2], bb[3]}};
;                 const f32x2 m2[4] = {{ma[0], ma[1]}, {ma[2], ma[3]}, {mb[0], mb[1]}, {mb[2], mb[3]}};
;                 const f32x2 r2[4] = {{ra[0], ra[1]}, {ra[2], ra[3]}, {rb[0], rb[1]}, {rb[2], rb[3]}};
;                 f32x2 accA = s[0][0] * k2[0], accB = s[1][0] * k2[0], accA2 = s[0][2] * k2[2], accB2 = s[1][2] * k2[2];
;                 accA = s[0][1] * k2[1] + accA; accB = s[1][1] * k2[1] + accB; accA2 = s[0][3] * k2[3] + accA2; accB2 = s[1][3] * k2[3] + accB2;
;                 accA = accA + accA2; accB = accB + accB2;
;                 float sa0 = accA.x + accA.y, sa1 = accB.x + accB.y;
;                 sa0 += dpp_f<0xB1>(sa0); sa1 += dpp_f<0xB1>(sa1);
;                 sa0 += dpp_f<0x4E>(sa0); sa1 += dpp_f<0x4E>(sa1);
;                 sa0 += dpp_f<0x141>(sa0); sa1 += dpp_f<0x141>(sa1);
;                 const f32x2 saA = {sa0, sa0}, saB = {sa1, sa1}, vA = {v01.x, v01.x}, vB = {v01.y, v01.y};
;                 f32x2 yA, yB;
; #pragma unroll
;                 for (int j = 0; j < 4; ++j) {
;                     f32x2 tA = vA * m2[j], tB = vB * m2[j];
;                     tA = saA * b2[j] + tA; tB = saB * b2[j] + tB;
;                     s[0][j] = s[0][j] * w2[j] + tA; s[1][j] = s[1][j] * w2[j] + tB;
	v_pk_mul_f32 v[20:21], v[2:3], v[110:111] op_sel_hi:[1,0]
	v_pk_mul_f32 v[22:23], v[10:11], v[114:115] op_sel_hi:[1,0]
	ds_read_b128 v[64:67], v180 offset:6144
	v_pk_fma_f32 v[20:21], v[4:5], v[110:111], v[20:21] op_sel:[0,1,0]
	v_pk_fma_f32 v[22:23], v[12:13], v[114:115], v[22:23] op_sel:[0,1,0]
	ds_read_b128 v[68:71], v180 offset:6160
	v_pk_fma_f32 v[20:21], v[6:7], v[112:113], v[20:21] op_sel_hi:[1,0,1]
	v_pk_fma_f32 v[22:23], v[14:15], v[116:117], v[22:23] op_sel_hi:[1,0,1]
	ds_read_b64 v[104:105], v181 offset:22528
	v_pk_fma_f32 v[20:21], v[8:9], v[112:113], v[20:21] op_sel:[0,1,0]
	v_pk_fma_f32 v[22:23], v[16:17], v[116:117], v[22:23] op_sel:[0,1,0]
	ds_read_b128 v[88:91], v180 offset:14336
	ds_read_b128 v[92:95], v180 offset:14352
	v_pk_add_f32 v[20:21], v[20:21], v[22:23]
	ds_read_b128 v[72:75], v180 offset:2048
	ds_read_b128 v[76:79], v180 offset:2064
	v_add_f32_dpp v20, v20, v20 quad_perm:[1,0,3,2] row_mask:0xf bank_mask:0xf bound_ctrl:1
	v_add_f32_dpp v21, v21, v21 quad_perm:[1,0,3,2] row_mask:0xf bank_mask:0xf bound_ctrl:1
	ds_read_b128 v[80:83], v180 offset:10240
	v_add_f32_dpp v20, v20, v20 quad_perm:[2,3,0,1] row_mask:0xf bank_mask:0xf bound_ctrl:1
	v_add_f32_dpp v21, v21, v21 quad_perm:[2,3,0,1] row_mask:0xf bank_mask:0xf bound_ctrl:1
	ds_read_b128 v[84:87], v180 offset:10256
	v_add_f32_dpp v20, v20, v20 row_half_mirror row_mask:0xf bank_mask:0xf bound_ctrl:1
	v_add_f32_dpp v21, v21, v21 row_half_mirror row_mask:0xf bank_mask:0xf bound_ctrl:1
	ds_read_b128 v[96:99], v180 offset:18432
	ds_read_b128 v[100:103], v180 offset:18448
	v_add_f32_dpp v40, v40, v40 quad_perm:[1,0,3,2] row_mask:0xf bank_mask:0xf bound_ctrl:1
	v_add_f32_dpp v41, v41, v41 quad_perm:[1,0,3,2] row_mask:0xf bank_mask:0xf bound_ctrl:1
	v_pk_mul_f32 v[24:25], v[150:151], v[134:135] op_sel_hi:[1,0]
	v_add_f32_dpp v40, v40, v40 quad_perm:[2,3,0,1] row_mask:0xf bank_mask:0xf bound_ctrl:1
	v_add_f32_dpp v41, v41, v41 quad_perm:[2,3,0,1] row_mask:0xf bank_mask:0xf bound_ctrl:1
	v_pk_fma_f32 v[24:25], v[2:3], v[118:119], v[24:25] op_sel_hi:[1,0,1]
	v_add_f32_dpp v40, v40, v40 row_half_mirror row_mask:0xf bank_mask:0xf bound_ctrl:1
	v_add_f32_dpp v41, v41, v41 row_half_mirror row_mask:0xf bank_mask:0xf bound_ctrl:1
	v_pk_fma_f32 v[2:3], v[20:21], v[126:127], v[24:25] op_sel_hi:[1,0,1]
	v_pk_mul_f32 v[26:27], v[150:151], v[134:135] op_sel:[0,1]
	ds_write_b64 v184, v[40:41] offset:30208
	v_pk_mul_f32 v[28:29], v[150:151], v[136:137] op_sel_hi:[1,0]
	v_pk_fma_f32 v[26:27], v[4:5], v[118:119], v[26:27] op_sel:[0,1,0]
	v_pk_mul_f32 v[30:31], v[150:151], v[136:137] op_sel:[0,1]
	v_pk_fma_f32 v[28:29], v[6:7], v[120:121], v[28:29] op_sel_hi:[1,0,1]
	v_pk_fma_f32 v[4:5], v[20:21], v[126:127], v[26:27] op_sel:[0,1,0]
	v_pk_fma_f32 v[30:31], v[8:9], v[120:121], v[30:31] op_sel:[0,1,0]
	v_pk_fma_f32 v[6:7], v[20:21], v[128:129], v[28:29] op_sel_hi:[1,0,1]
	v_pk_mul_f32 v[32:33], v[150:151], v[138:139] op_sel_hi:[1,0]
	v_pk_fma_f32 v[8:9], v[20:21], v[128:129], v[30:31] op_sel:[0,1,0]
	v_pk_mul_f32 v[34:35], v[150:151], v[138:139] op_sel:[0,1]
	v_pk_fma_f32 v[32:33], v[10:11], v[122:123], v[32:33] op_sel_hi:[1,0,1]
	v_pk_mul_f32 v[36:37], v[150:151], v[140:141] op_sel_hi:[1,0]
	v_pk_fma_f32 v[34:35], v[12:13], v[122:123], v[34:35] op_sel:[0,1,0]
	v_pk_fma_f32 v[10:11], v[20:21], v[130:131], v[32:33] op_sel_hi:[1,0,1]
	v_pk_fma_f32 v[36:37], v[14:15], v[124:125], v[36:37] op_sel_hi:[1,0,1]
	v_pk_fma_f32 v[12:13], v[20:21], v[130:131], v[34:35] op_sel:[0,1,0]
	v_pk_mul_f32 v[38:39], v[150:151], v[140:141] op_sel:[0,1]
	v_pk_fma_f32 v[14:15], v[20:21], v[132:133], v[36:37] op_sel_hi:[1,0,1]
	v_pk_mul_f32 v[42:43], v[2:3], v[142:143] op_sel_hi:[1,0]
	v_pk_fma_f32 v[38:39], v[16:17], v[124:125], v[38:39] op_sel:[0,1,0]
	v_pk_mul_f32 v[44:45], v[10:11], v[146:147] op_sel_hi:[1,0]
	v_pk_fma_f32 v[42:43], v[4:5], v[142:143], v[42:43] op_sel:[0,1,0]
	v_pk_fma_f32 v[16:17], v[20:21], v[132:133], v[38:39] op_sel:[0,1,0]
	v_pk_fma_f32 v[44:45], v[12:13], v[146:147], v[44:45] op_sel:[0,1,0]
	v_pk_fma_f32 v[42:43], v[6:7], v[144:145], v[42:43] op_sel_hi:[1,0,1]
	v_pk_fma_f32 v[44:45], v[14:15], v[148:149], v[44:45] op_sel_hi:[1,0,1]
	v_pk_fma_f32 v[42:43], v[8:9], v[144:145], v[42:43] op_sel:[0,1,0]
	v_pk_fma_f32 v[44:45], v[16:17], v[148:149], v[44:45] op_sel:[0,1,0]
	v_pk_add_f32 v[42:43], v[42:43], v[44:45]
	s_waitcnt lgkmcnt(0)
; __device__ __forceinline__ void rwkv_block(KP p, int o, int b, int hd, LAS unsigned char* lds, const bf16_t* P, bf16_t* YB) {
;     ...
;             for (int tt = 0; tt < 16; ++tt) {
;                 const int o8 = tt * 64 + c * 8;
;                 const f32x4 ka = *(const LAS f32x4*)(KK + o8), kb = *(const LAS f32x4*)(KK + o8 + 4);
;                 const f32x4 wa = *(const LAS f32x4*)(Wd + o8), wb = *(const LAS f32x4*)(Wd + o8 + 4);
;                 const f32x4 ba = *(const LAS f32x4*)(BB + o8), bb = *(const LAS f32x4*)(BB + o8 + 4);
;                 const f32x4 ma = *(const LAS f32x4*)(KM + o8), mb = *(const LAS f32x4*)(KM + o8 + 4);
;                 const f32x4 ra = *(const LAS f32x4*)(Rr + o8), rb = *(const LAS f32x4*)(Rr + o8 + 4);
;                 const f32x2 v01 = *(const LAS f32x2*)(Vv + tt * 64 + 2 * rp);
;                 const f32x2 k2[4] = {{ka[0], ka[1]}, {ka[2], ka[3]}, {kb[0], kb[1]}, {kb[2], kb[3]}};
;                 const f32x2 w2[4] = {{wa[0], wa[1]}, {wa[2], wa[3]}, {wb[0], wb[1]}, {wb[2], wb[3]}};
;                 const f32x2 b2[4] = {{ba[0], ba[1]}, {ba[2], ba[3]}, {bb[0], bb[1]}, {bb[2], bb[3]}};
;                 const f32x2 m2[4] = {{ma[0], ma[1]}, {ma[2], ma[3]}, {mb[0], mb[1]}, {mb[2], mb[3]}};
;                 const f32x2 r2[4] = {{ra[0], ra[1]}, {ra[2], ra[3]}, {rb[0], rb[1]}, {rb[2], rb[3]}};
;                 f32x2 accA = s[0][0] * k2[0], accB = s[1][0] * k2[0], accA2 = s[0][2] * k2[2], accB2 = s[1][2] * k2[2];
;                 accA = s[0][1] * k2[1] + accA; accB = s[1][1] * k2[1] + accB; accA2 = s[0][3] * k2[3] + accA2; accB2 = s[1][3] * k2[3] + accB2;
;                 accA = accA + accA2; accB = accB + accB2;
;                 float sa0 = accA.x + accA.y, sa1 = accB.x + accB.y;
;                 sa0 += dpp_f<0xB1>(sa0); sa1 += dpp_f<0xB1>(sa1);
;                 sa0 += dpp_f<0x4E>(sa0); sa1 += dpp_f<0x4E>(sa1);
;                 sa0 += dpp_f<0x141>(sa0); sa1 += dpp_f<0x141>(sa1);
;                 const f32x2 saA = {sa0, sa0}, saB = {sa1, sa1}, vA = {v01.x, v01.x}, vB = {v01.y, v01.y};
;                 f32x2 yA, yB;
; #pragma unroll
;                 for (int j = 0; j < 4; ++j) {
;                     f32x2 tA = vA * m2[j], tB = vB * m2[j];
;                     tA = saA * b2[j] + tA; tB = saB * b2[j] + tB;
;                     s[0][j] = s[0][j] * w2[j] + tA; s[1][j] = s[1][j] * w2[j] + tB;
	v_pk_mul_f32 v[20:21], v[2:3], v[64:65] op_sel_hi:[1,0]
	v_pk_mul_f32 v[22:23], v[10:11], v[68:69] op_sel_hi:[1,0]
	ds_read_b128 v[110:113], v180 offset:6400
	v_pk_fma_f32 v[20:21], v[4:5], v[64:65], v[20:21] op_sel:[0,1,0]
	v_pk_fma_f32 v[22:23], v[12:13], v[68:69], v[22:23] op_sel:[0,1,0]
	ds_read_b128 v[114:117], v180 offset:6416
	v_pk_fma_f32 v[20:21], v[6:7], v[66:67], v[20:21] op_sel_hi:[1,0,1]
	v_pk_fma_f32 v[22:23], v[14:15], v[70:71], v[22:23] op_sel_hi:[1,0,1]
	ds_read_b64 v[150:151], v181 offset:22784
	v_pk_fma_f32 v[20:21], v[8:9], v[66:67], v[20:21] op_sel:[0,1,0]
	v_pk_fma_f32 v[22:23], v[16:17], v[70:71], v[22:23] op_sel:[0,1,0]
	ds_read_b128 v[134:137], v180 offset:14592
	ds_read_b128 v[138:141], v180 offset:14608
	v_pk_add_f32 v[20:21], v[20:21], v[22:23]
	ds_read_b128 v[118:121], v180 offset:2304
	ds_read_b128 v[122:125], v180 offset:2320
	v_add_f32_dpp v20, v20, v20 quad_perm:[1,0,3,2] row_mask:0xf bank_mask:0xf bound_ctrl:1
	v_add_f32_dpp v21, v21, v21 quad_perm:[1,0,3,2] row_mask:0xf bank_mask:0xf bound_ctrl:1
	ds_read_b128 v[126:129], v180 offset:10496
	v_add_f32_dpp v20, v20, v20 quad_perm:[2,3,0,1] row_mask:0xf bank_mask:0xf bound_ctrl:1
	v_add_f32_dpp v21, v21, v21 quad_perm:[2,3,0,1] row_mask:0xf bank_mask:0xf bound_ctrl:1
	ds_read_b128 v[130:133], v180 offset:10512
	v_add_f32_dpp v20, v20, v20 row_half_mirror row_mask:0xf bank_mask:0xf bound_ctrl:1
	v_add_f32_dpp v21, v21, v21 row_half_mirror row_mask:0xf bank_mask:0xf bound_ctrl:1
	ds_read_b128 v[142:145], v180 offset:18688
	ds_read_b128 v[146:149], v180 offset:18704
	v_add_f32_dpp v42, v42, v42 quad_perm:[1,0,3,2] row_mask:0xf bank_mask:0xf bound_ctrl:1
	v_add_f32_dpp v43, v43, v43 quad_perm:[1,0,3,2] row_mask:0xf bank_mask:0xf bound_ctrl:1
	v_pk_mul_f32 v[24:25], v[104:105], v[88:89] op_sel_hi:[1,0]
	v_add_f32_dpp v42, v42, v42 quad_perm:[2,3,0,1] row_mask:0xf bank_mask:0xf bound_ctrl:1
	v_add_f32_dpp v43, v43, v43 quad_perm:[2,3,0,1] row_mask:0xf bank_mask:0xf bound_ctrl:1
	v_pk_fma_f32 v[24:25], v[2:3], v[72:73], v[24:25] op_sel_hi:[1,0,1]
	v_add_f32_dpp v42, v42, v42 row_half_mirror row_mask:0xf bank_mask:0xf bound_ctrl:1
	v_add_f32_dpp v43, v43, v43 row_half_mirror row_mask:0xf bank_mask:0xf bound_ctrl:1
	v_pk_fma_f32 v[2:3], v[20:21], v[80:81], v[24:25] op_sel_hi:[1,0,1]
	v_pk_mul_f32 v[26:27], v[104:105], v[88:89] op_sel:[0,1]
	ds_write_b64 v184, v[42:43] offset:30464
	v_pk_mul_f32 v[28:29], v[104:105], v[90:91] op_sel_hi:[1,0]
	v_pk_fma_f32 v[26:27], v[4:5], v[72:73], v[26:27] op_sel:[0,1,0]
	v_pk_mul_f32 v[30:31], v[104:105], v[90:91] op_sel:[0,1]
	v_pk_fma_f32 v[28:29], v[6:7], v[74:75], v[28:29] op_sel_hi:[1,0,1]
	v_pk_fma_f32 v[4:5], v[20:21], v[80:81], v[26:27] op_sel:[0,1,0]
	v_pk_fma_f32 v[30:31], v[8:9], v[74:75], v[30:31] op_sel:[0,1,0]
	v_pk_fma_f32 v[6:7], v[20:21], v[82:83], v[28:29] op_sel_hi:[1,0,1]
	v_pk_mul_f32 v[32:33], v[104:105], v[92:93] op_sel_hi:[1,0]
	v_pk_fma_f32 v[8:9], v[20:21], v[82:83], v[30:31] op_sel:[0,1,0]
	v_pk_mul_f32 v[34:35], v[104:105], v[92:93] op_sel:[0,1]
	v_pk_fma_f32 v[32:33], v[10:11], v[76:77], v[32:33] op_sel_hi:[1,0,1]
	v_pk_mul_f32 v[36:37], v[104:105], v[94:95] op_sel_hi:[1,0]
	v_pk_fma_f32 v[34:35], v[12:13], v[76:77], v[34:35] op_sel:[0,1,0]
	v_pk_fma_f32 v[10:11], v[20:21], v[84:85], v[32:33] op_sel_hi:[1,0,1]
	v_pk_fma_f32 v[36:37], v[14:15], v[78:79], v[36:37] op_sel_hi:[1,0,1]
	v_pk_fma_f32 v[12:13], v[20:21], v[84:85], v[34:35] op_sel:[0,1,0]
	v_pk_mul_f32 v[38:39], v[104:105], v[94:95] op_sel:[0,1]
	v_pk_fma_f32 v[14:15], v[20:21], v[86:87], v[36:37] op_sel_hi:[1,0,1]
	v_pk_mul_f32 v[40:41], v[2:3], v[96:97] op_sel_hi:[1,0]
	v_pk_fma_f32 v[38:39], v[16:17], v[78:79], v[38:39] op_sel:[0,1,0]
	v_pk_mul_f32 v[44:45], v[10:11], v[100:101] op_sel_hi:[1,0]
	v_pk_fma_f32 v[40:41], v[4:5], v[96:97], v[40:41] op_sel:[0,1,0]
	v_pk_fma_f32 v[16:17], v[20:21], v[86:87], v[38:39] op_sel:[0,1,0]
	v_pk_fma_f32 v[44:45], v[12:13], v[100:101], v[44:45] op_sel:[0,1,0]
	v_pk_fma_f32 v[40:41], v[6:7], v[98:99], v[40:41] op_sel_hi:[1,0,1]
	v_pk_fma_f32 v[44:45], v[14:15], v[102:103], v[44:45] op_sel_hi:[1,0,1]
	v_pk_fma_f32 v[40:41], v[8:9], v[98:99], v[40:41] op_sel:[0,1,0]
	v_pk_fma_f32 v[44:45], v[16:17], v[102:103], v[44:45] op_sel:[0,1,0]
	v_pk_add_f32 v[40:41], v[40:41], v[44:45]
	s_waitcnt lgkmcnt(0)
; __device__ __forceinline__ void rwkv_block(KP p, int o, int b, int hd, LAS unsigned char* lds, const bf16_t* P, bf16_t* YB) {
;     ...
;             for (int tt = 0; tt < 16; ++tt) {
;                 const int o8 = tt * 64 + c * 8;
;                 const f32x4 ka = *(const LAS f32x4*)(KK + o8), kb = *(const LAS f32x4*)(KK + o8 + 4);
;                 const f32x4 wa = *(const LAS f32x4*)(Wd + o8), wb = *(const LAS f32x4*)(Wd + o8 + 4);
;                 const f32x4 ba = *(const LAS f32x4*)(BB + o8), bb = *(const LAS f32x4*)(BB + o8 + 4);
;                 const f32x4 ma = *(const LAS f32x4*)(KM + o8), mb = *(const LAS f32x4*)(KM + o8 + 4);
;                 const f32x4 ra = *(const LAS f32x4*)(Rr + o8), rb = *(const LAS f32x4*)(Rr + o8 + 4);
;                 const f32x2 v01 = *(const LAS f32x2*)(Vv + tt * 64 + 2 * rp);
;                 const f32x2 k2[4] = {{ka[0], ka[1]}, {ka[2], ka[3]}, {kb[0], kb[1]}, {kb[2], kb[3]}};
;                 const f32x2 w2[4] = {{wa[0], wa[1]}, {wa[2], wa[3]}, {wb[0], wb[1]}, {wb[2], wb[3]}};
;                 const f32x2 b2[4] = {{ba[0], ba[1]}, {ba[2], ba[3]}, {bb[0], bb[1]}, {bb[2], bb[3]}};
;                 const f32x2 m2[4] = {{ma[0], ma[1]}, {ma[2], ma[3]}, {mb[0], mb[1]}, {mb[2], mb[3]}};
;                 const f32x2 r2[4] = {{ra[0], ra[1]}, {ra[2], ra[3]}, {rb[0], rb[1]}, {rb[2], rb[3]}};
;                 f32x2 accA = s[0][0] * k2[0], accB = s[1][0] * k2[0], accA2 = s[0][2] * k2[2], accB2 = s[1][2] * k2[2];
;                 accA = s[0][1] * k2[1] + accA; accB = s[1][1] * k2[1] + accB; accA2 = s[0][3] * k2[3] + accA2; accB2 = s[1][3] * k2[3] + accB2;
;                 accA = accA + accA2; accB = accB + accB2;
;                 float sa0 = accA.x + accA.y, sa1 = accB.x + accB.y;
;                 sa0 += dpp_f<0xB1>(sa0); sa1 += dpp_f<0xB1>(sa1);
;                 sa0 += dpp_f<0x4E>(sa0); sa1 += dpp_f<0x4E>(sa1);
;                 sa0 += dpp_f<0x141>(sa0); sa1 += dpp_f<0x141>(sa1);
;                 const f32x2 saA = {sa0, sa0}, saB = {sa1, sa1}, vA = {v01.x, v01.x}, vB = {v01.y, v01.y};
;                 f32x2 yA, yB;
; #pragma unroll
;                 for (int j = 0; j < 4; ++j) {
;                     f32x2 tA = vA * m2[j], tB = vB * m2[j];
;                     tA = saA * b2[j] + tA; tB = saB * b2[j] + tB;
;                     s[0][j] = s[0][j] * w2[j] + tA; s[1][j] = s[1][j] * w2[j] + tB;
	v_pk_mul_f32 v[20:21], v[2:3], v[110:111] op_sel_hi:[1,0]
	v_pk_mul_f32 v[22:23], v[10:11], v[114:115] op_sel_hi:[1,0]
	ds_read_b128 v[64:67], v180 offset:6656
	v_pk_fma_f32 v[20:21], v[4:5], v[110:111], v[20:21] op_sel:[0,1,0]
	v_pk_fma_f32 v[22:23], v[12:13], v[114:115], v[22:23] op_sel:[0,1,0]
	ds_read_b128 v[68:71], v180 offset:6672
	v_pk_fma_f32 v[20:21], v[6:7], v[112:113], v[20:21] op_sel_hi:[1,0,1]
	v_pk_fma_f32 v[22:23], v[14:15], v[116:117], v[22:23] op_sel_hi:[1,0,1]
	ds_read_b64 v[104:105], v181 offset:23040
	v_pk_fma_f32 v[20:21], v[8:9], v[112:113], v[20:21] op_sel:[0,1,0]
	v_pk_fma_f32 v[22:23], v[16:17], v[116:117], v[22:23] op_sel:[0,1,0]
	ds_read_b128 v[88:91], v180 offset:14848
	ds_read_b128 v[92:95], v180 offset:14864
	v_pk_add_f32 v[20:21], v[20:21], v[22:23]
	ds_read_b128 v[72:75], v180 offset:2560
	ds_read_b128 v[76:79], v180 offset:2576
	v_add_f32_dpp v20, v20, v20 quad_perm:[1,0,3,2] row_mask:0xf bank_mask:0xf bound_ctrl:1
	v_add_f32_dpp v21, v21, v21 quad_perm:[1,0,3,2] row_mask:0xf bank_mask:0xf bound_ctrl:1
	ds_read_b128 v[80:83], v180 offset:10752
	v_add_f32_dpp v20, v20, v20 quad_perm:[2,3,0,1] row_mask:0xf bank_mask:0xf bound_ctrl:1
	v_add_f32_dpp v21, v21, v21 quad_perm:[2,3,0,1] row_mask:0xf bank_mask:0xf bound_ctrl:1
	ds_read_b128 v[84:87], v180 offset:10768
	v_add_f32_dpp v20, v20, v20 row_half_mirror row_mask:0xf bank_mask:0xf bound_ctrl:1
	v_add_f32_dpp v21, v21, v21 row_half_mirror row_mask:0xf bank_mask:0xf bound_ctrl:1
	ds_read_b128 v[96:99], v180 offset:18944
	ds_read_b128 v[100:103], v180 offset:18960
	v_add_f32_dpp v40, v40, v40 quad_perm:[1,0,3,2] row_mask:0xf bank_mask:0xf bound_ctrl:1
	v_add_f32_dpp v41, v41, v41 quad_perm:[1,0,3,2] row_mask:0xf bank_mask:0xf bound_ctrl:1
	v_pk_mul_f32 v[24:25], v[150:151], v[134:135] op_sel_hi:[1,0]
	v_add_f32_dpp v40, v40, v40 quad_perm:[2,3,0,1] row_mask:0xf bank_mask:0xf bound_ctrl:1
	v_add_f32_dpp v41, v41, v41 quad_perm:[2,3,0,1] row_mask:0xf bank_mask:0xf bound_ctrl:1
	v_pk_fma_f32 v[24:25], v[2:3], v[118:119], v[24:25] op_sel_hi:[1,0,1]
	v_add_f32_dpp v40, v40, v40 row_half_mirror row_mask:0xf bank_mask:0xf bound_ctrl:1
	v_add_f32_dpp v41, v41, v41 row_half_mirror row_mask:0xf bank_mask:0xf bound_ctrl:1
	v_pk_fma_f32 v[2:3], v[20:21], v[126:127], v[24:25] op_sel_hi:[1,0,1]
	v_pk_mul_f32 v[26:27], v[150:151], v[134:135] op_sel:[0,1]
	ds_write_b64 v184, v[40:41] offset:30720
	v_pk_mul_f32 v[28:29], v[150:151], v[136:137] op_sel_hi:[1,0]
	v_pk_fma_f32 v[26:27], v[4:5], v[118:119], v[26:27] op_sel:[0,1,0]
	v_pk_mul_f32 v[30:31], v[150:151], v[136:137] op_sel:[0,1]
	v_pk_fma_f32 v[28:29], v[6:7], v[120:121], v[28:29] op_sel_hi:[1,0,1]
	v_pk_fma_f32 v[4:5], v[20:21], v[126:127], v[26:27] op_sel:[0,1,0]
	v_pk_fma_f32 v[30:31], v[8:9], v[120:121], v[30:31] op_sel:[0,1,0]
	v_pk_fma_f32 v[6:7], v[20:21], v[128:129], v[28:29] op_sel_hi:[1,0,1]
	v_pk_mul_f32 v[32:33], v[150:151], v[138:139] op_sel_hi:[1,0]
	v_pk_fma_f32 v[8:9], v[20:21], v[128:129], v[30:31] op_sel:[0,1,0]
	v_pk_mul_f32 v[34:35], v[150:151], v[138:139] op_sel:[0,1]
	v_pk_fma_f32 v[32:33], v[10:11], v[122:123], v[32:33] op_sel_hi:[1,0,1]
	v_pk_mul_f32 v[36:37], v[150:151], v[140:141] op_sel_hi:[1,0]
	v_pk_fma_f32 v[34:35], v[12:13], v[122:123], v[34:35] op_sel:[0,1,0]
	v_pk_fma_f32 v[10:11], v[20:21], v[130:131], v[32:33] op_sel_hi:[1,0,1]
	v_pk_fma_f32 v[36:37], v[14:15], v[124:125], v[36:37] op_sel_hi:[1,0,1]
	v_pk_fma_f32 v[12:13], v[20:21], v[130:131], v[34:35] op_sel:[0,1,0]
	v_pk_mul_f32 v[38:39], v[150:151], v[140:141] op_sel:[0,1]
	v_pk_fma_f32 v[14:15], v[20:21], v[132:133], v[36:37] op_sel_hi:[1,0,1]
	v_pk_mul_f32 v[42:43], v[2:3], v[142:143] op_sel_hi:[1,0]
	v_pk_fma_f32 v[38:39], v[16:17], v[124:125], v[38:39] op_sel:[0,1,0]
	v_pk_mul_f32 v[44:45], v[10:11], v[146:147] op_sel_hi:[1,0]
	v_pk_fma_f32 v[42:43], v[4:5], v[142:143], v[42:43] op_sel:[0,1,0]
	v_pk_fma_f32 v[16:17], v[20:21], v[132:133], v[38:39] op_sel:[0,1,0]
	v_pk_fma_f32 v[44:45], v[12:13], v[146:147], v[44:45] op_sel:[0,1,0]
	v_pk_fma_f32 v[42:43], v[6:7], v[144:145], v[42:43] op_sel_hi:[1,0,1]
	v_pk_fma_f32 v[44:45], v[14:15], v[148:149], v[44:45] op_sel_hi:[1,0,1]
	v_pk_fma_f32 v[42:43], v[8:9], v[144:145], v[42:43] op_sel:[0,1,0]
	v_pk_fma_f32 v[44:45], v[16:17], v[148:149], v[44:45] op_sel:[0,1,0]
	v_pk_add_f32 v[42:43], v[42:43], v[44:45]
	s_waitcnt lgkmcnt(0)
; __device__ __forceinline__ void rwkv_block(KP p, int o, int b, int hd, LAS unsigned char* lds, const bf16_t* P, bf16_t* YB) {
;     ...
;             for (int tt = 0; tt < 16; ++tt) {
;                 const int o8 = tt * 64 + c * 8;
;                 const f32x4 ka = *(const LAS f32x4*)(KK + o8), kb = *(const LAS f32x4*)(KK + o8 + 4);
;                 const f32x4 wa = *(const LAS f32x4*)(Wd + o8), wb = *(const LAS f32x4*)(Wd + o8 + 4);
;                 const f32x4 ba = *(const LAS f32x4*)(BB + o8), bb = *(const LAS f32x4*)(BB + o8 + 4);
;                 const f32x4 ma = *(const LAS f32x4*)(KM + o8), mb = *(const LAS f32x4*)(KM + o8 + 4);
;                 const f32x4 ra = *(const LAS f32x4*)(Rr + o8), rb = *(const LAS f32x4*)(Rr + o8 + 4);
;                 const f32x2 v01 = *(const LAS f32x2*)(Vv + tt * 64 + 2 * rp);
;                 const f32x2 k2[4] = {{ka[0], ka[1]}, {ka[2], ka[3]}, {kb[0], kb[1]}, {kb[2], kb[3]}};
;                 const f32x2 w2[4] = {{wa[0], wa[1]}, {wa[2], wa[3]}, {wb[0], wb[1]}, {wb[2], wb[3]}};
;                 const f32x2 b2[4] = {{ba[0], ba[1]}, {ba[2], ba[3]}, {bb[0], bb[1]}, {bb[2], bb[3]}};
;                 const f32x2 m2[4] = {{ma[0], ma[1]}, {ma[2], ma[3]}, {mb[0], mb[1]}, {mb[2], mb[3]}};
;                 const f32x2 r2[4] = {{ra[0], ra[1]}, {ra[2], ra[3]}, {rb[0], rb[1]}, {rb[2], rb[3]}};
;                 f32x2 accA = s[0][0] * k2[0], accB = s[1][0] * k2[0], accA2 = s[0][2] * k2[2], accB2 = s[1][2] * k2[2];
;                 accA = s[0][1] * k2[1] + accA; accB = s[1][1] * k2[1] + accB; accA2 = s[0][3] * k2[3] + accA2; accB2 = s[1][3] * k2[3] + accB2;
;                 accA = accA + accA2; accB = accB + accB2;
;                 float sa0 = accA.x + accA.y, sa1 = accB.x + accB.y;
;                 sa0 += dpp_f<0xB1>(sa0); sa1 += dpp_f<0xB1>(sa1);
;                 sa0 += dpp_f<0x4E>(sa0); sa1 += dpp_f<0x4E>(sa1);
;                 sa0 += dpp_f<0x141>(sa0); sa1 += dpp_f<0x141>(sa1);
;                 const f32x2 saA = {sa0, sa0}, saB = {sa1, sa1}, vA = {v01.x, v01.x}, vB = {v01.y, v01.y};
;                 f32x2 yA, yB;
; #pragma unroll
;                 for (int j = 0; j < 4; ++j) {
;                     f32x2 tA = vA * m2[j], tB = vB * m2[j];
;                     tA = saA * b2[j] + tA; tB = saB * b2[j] + tB;
;                     s[0][j] = s[0][j] * w2[j] + tA; s[1][j] = s[1][j] * w2[j] + tB;
	v_pk_mul_f32 v[20:21], v[2:3], v[64:65] op_sel_hi:[1,0]
	v_pk_mul_f32 v[22:23], v[10:11], v[68:69] op_sel_hi:[1,0]
	ds_read_b128 v[110:113], v180 offset:6912
	v_pk_fma_f32 v[20:21], v[4:5], v[64:65], v[20:21] op_sel:[0,1,0]
	v_pk_fma_f32 v[22:23], v[12:13], v[68:69], v[22:23] op_sel:[0,1,0]
	ds_read_b128 v[114:117], v180 offset:6928
	v_pk_fma_f32 v[20:21], v[6:7], v[66:67], v[20:21] op_sel_hi:[1,0,1]
	v_pk_fma_f32 v[22:23], v[14:15], v[70:71], v[22:23] op_sel_hi:[1,0,1]
	ds_read_b64 v[150:151], v181 offset:23296
	v_pk_fma_f32 v[20:21], v[8:9], v[66:67], v[20:21] op_sel:[0,1,0]
	v_pk_fma_f32 v[22:23], v[16:17], v[70:71], v[22:23] op_sel:[0,1,0]
	ds_read_b128 v[134:137], v180 offset:15104
	ds_read_b128 v[138:141], v180 offset:15120
	v_pk_add_f32 v[20:21], v[20:21], v[22:23]
	ds_read_b128 v[118:121], v180 offset:2816
	ds_read_b128 v[122:125], v180 offset:2832
	v_add_f32_dpp v20, v20, v20 quad_perm:[1,0,3,2] row_mask:0xf bank_mask:0xf bound_ctrl:1
	v_add_f32_dpp v21, v21, v21 quad_perm:[1,0,3,2] row_mask:0xf bank_mask:0xf bound_ctrl:1
	ds_read_b128 v[126:129], v180 offset:11008
	v_add_f32_dpp v20, v20, v20 quad_perm:[2,3,0,1] row_mask:0xf bank_mask:0xf bound_ctrl:1
	v_add_f32_dpp v21, v21, v21 quad_perm:[2,3,0,1] row_mask:0xf bank_mask:0xf bound_ctrl:1
	ds_read_b128 v[130:133], v180 offset:11024
	v_add_f32_dpp v20, v20, v20 row_half_mirror row_mask:0xf bank_mask:0xf bound_ctrl:1
	v_add_f32_dpp v21, v21, v21 row_half_mirror row_mask:0xf bank_mask:0xf bound_ctrl:1
	ds_read_b128 v[142:145], v180 offset:19200
	ds_read_b128 v[146:149], v180 offset:19216
	v_add_f32_dpp v42, v42, v42 quad_perm:[1,0,3,2] row_mask:0xf bank_mask:0xf bound_ctrl:1
	v_add_f32_dpp v43, v43, v43 quad_perm:[1,0,3,2] row_mask:0xf bank_mask:0xf bound_ctrl:1
	v_pk_mul_f32 v[24:25], v[104:105], v[88:89] op_sel_hi:[1,0]
	v_add_f32_dpp v42, v42, v42 quad_perm:[2,3,0,1] row_mask:0xf bank_mask:0xf bound_ctrl:1
	v_add_f32_dpp v43, v43, v43 quad_perm:[2,3,0,1] row_mask:0xf bank_mask:0xf bound_ctrl:1
	v_pk_fma_f32 v[24:25], v[2:3], v[72:73], v[24:25] op_sel_hi:[1,0,1]
	v_add_f32_dpp v42, v42, v42 row_half_mirror row_mask:0xf bank_mask:0xf bound_ctrl:1
	v_add_f32_dpp v43, v43, v43 row_half_mirror row_mask:0xf bank_mask:0xf bound_ctrl:1
	v_pk_fma_f32 v[2:3], v[20:21], v[80:81], v[24:25] op_sel_hi:[1,0,1]
	v_pk_mul_f32 v[26:27], v[104:105], v[88:89] op_sel:[0,1]
	ds_write_b64 v184, v[42:43] offset:30976
	v_pk_mul_f32 v[28:29], v[104:105], v[90:91] op_sel_hi:[1,0]
	v_pk_fma_f32 v[26:27], v[4:5], v[72:73], v[26:27] op_sel:[0,1,0]
	v_pk_mul_f32 v[30:31], v[104:105], v[90:91] op_sel:[0,1]
	v_pk_fma_f32 v[28:29], v[6:7], v[74:75], v[28:29] op_sel_hi:[1,0,1]
	v_pk_fma_f32 v[4:5], v[20:21], v[80:81], v[26:27] op_sel:[0,1,0]
	v_pk_fma_f32 v[30:31], v[8:9], v[74:75], v[30:31] op_sel:[0,1,0]
	v_pk_fma_f32 v[6:7], v[20:21], v[82:83], v[28:29] op_sel_hi:[1,0,1]
	v_pk_mul_f32 v[32:33], v[104:105], v[92:93] op_sel_hi:[1,0]
	v_pk_fma_f32 v[8:9], v[20:21], v[82:83], v[30:31] op_sel:[0,1,0]
	v_pk_mul_f32 v[34:35], v[104:105], v[92:93] op_sel:[0,1]
	v_pk_fma_f32 v[32:33], v[10:11], v[76:77], v[32:33] op_sel_hi:[1,0,1]
	v_pk_mul_f32 v[36:37], v[104:105], v[94:95] op_sel_hi:[1,0]
	v_pk_fma_f32 v[34:35], v[12:13], v[76:77], v[34:35] op_sel:[0,1,0]
	v_pk_fma_f32 v[10:11], v[20:21], v[84:85], v[32:33] op_sel_hi:[1,0,1]
	v_pk_fma_f32 v[36:37], v[14:15], v[78:79], v[36:37] op_sel_hi:[1,0,1]
	v_pk_fma_f32 v[12:13], v[20:21], v[84:85], v[34:35] op_sel:[0,1,0]
	v_pk_mul_f32 v[38:39], v[104:105], v[94:95] op_sel:[0,1]
	v_pk_fma_f32 v[14:15], v[20:21], v[86:87], v[36:37] op_sel_hi:[1,0,1]
	v_pk_mul_f32 v[40:41], v[2:3], v[96:97] op_sel_hi:[1,0]
	v_pk_fma_f32 v[38:39], v[16:17], v[78:79], v[38:39] op_sel:[0,1,0]
	v_pk_mul_f32 v[44:45], v[10:11], v[100:101] op_sel_hi:[1,0]
	v_pk_fma_f32 v[40:41], v[4:5], v[96:97], v[40:41] op_sel:[0,1,0]
	v_pk_fma_f32 v[16:17], v[20:21], v[86:87], v[38:39] op_sel:[0,1,0]
	v_pk_fma_f32 v[44:45], v[12:13], v[100:101], v[44:45] op_sel:[0,1,0]
	v_pk_fma_f32 v[40:41], v[6:7], v[98:99], v[40:41] op_sel_hi:[1,0,1]
	v_pk_fma_f32 v[44:45], v[14:15], v[102:103], v[44:45] op_sel_hi:[1,0,1]
	v_pk_fma_f32 v[40:41], v[8:9], v[98:99], v[40:41] op_sel:[0,1,0]
	v_pk_fma_f32 v[44:45], v[16:17], v[102:103], v[44:45] op_sel:[0,1,0]
	v_pk_add_f32 v[40:41], v[40:41], v[44:45]
	s_waitcnt lgkmcnt(0)
; __device__ __forceinline__ void rwkv_block(KP p, int o, int b, int hd, LAS unsigned char* lds, const bf16_t* P, bf16_t* YB) {
;     ...
;             for (int tt = 0; tt < 16; ++tt) {
;                 const int o8 = tt * 64 + c * 8;
;                 const f32x4 ka = *(const LAS f32x4*)(KK + o8), kb = *(const LAS f32x4*)(KK + o8 + 4);
;                 const f32x4 wa = *(const LAS f32x4*)(Wd + o8), wb = *(const LAS f32x4*)(Wd + o8 + 4);
;                 const f32x4 ba = *(const LAS f32x4*)(BB + o8), bb = *(const LAS f32x4*)(BB + o8 + 4);
;                 const f32x4 ma = *(const LAS f32x4*)(KM + o8), mb = *(const LAS f32x4*)(KM + o8 + 4);
;                 const f32x4 ra = *(const LAS f32x4*)(Rr + o8), rb = *(const LAS f32x4*)(Rr + o8 + 4);
;                 const f32x2 v01 = *(const LAS f32x2*)(Vv + tt * 64 + 2 * rp);
;                 const f32x2 k2[4] = {{ka[0], ka[1]}, {ka[2], ka[3]}, {kb[0], kb[1]}, {kb[2], kb[3]}};
;                 const f32x2 w2[4] = {{wa[0], wa[1]}, {wa[2], wa[3]}, {wb[0], wb[1]}, {wb[2], wb[3]}};
;                 const f32x2 b2[4] = {{ba[0], ba[1]}, {ba[2], ba[3]}, {bb[0], bb[1]}, {bb[2], bb[3]}};
;                 const f32x2 m2[4] = {{ma[0], ma[1]}, {ma[2], ma[3]}, {mb[0], mb[1]}, {mb[2], mb[3]}};
;                 const f32x2 r2[4] = {{ra[0], ra[1]}, {ra[2], ra[3]}, {rb[0], rb[1]}, {rb[2], rb[3]}};
;                 f32x2 accA = s[0][0] * k2[0], accB = s[1][0] * k2[0], accA2 = s[0][2] * k2[2], accB2 = s[1][2] * k2[2];
;                 accA = s[0][1] * k2[1] + accA; accB = s[1][1] * k2[1] + accB; accA2 = s[0][3] * k2[3] + accA2; accB2 = s[1][3] * k2[3] + accB2;
;                 accA = accA + accA2; accB = accB + accB2;
;                 float sa0 = accA.x + accA.y, sa1 = accB.x + accB.y;
;                 sa0 += dpp_f<0xB1>(sa0); sa1 += dpp_f<0xB1>(sa1);
;                 sa0 += dpp_f<0x4E>(sa0); sa1 += dpp_f<0x4E>(sa1);
;                 sa0 += dpp_f<0x141>(sa0); sa1 += dpp_f<0x141>(sa1);
;                 const f32x2 saA = {sa0, sa0}, saB = {sa1, sa1}, vA = {v01.x, v01.x}, vB = {v01.y, v01.y};
;                 f32x2 yA, yB;
; #pragma unroll
;                 for (int j = 0; j < 4; ++j) {
;                     f32x2 tA = vA * m2[j], tB = vB * m2[j];
;                     tA = saA * b2[j] + tA; tB = saB * b2[j] + tB;
;                     s[0][j] = s[0][j] * w2[j] + tA; s[1][j] = s[1][j] * w2[j] + tB;
	v_pk_mul_f32 v[20:21], v[2:3], v[110:111] op_sel_hi:[1,0]
	v_pk_mul_f32 v[22:23], v[10:11], v[114:115] op_sel_hi:[1,0]
	ds_read_b128 v[64:67], v180 offset:7168
	v_pk_fma_f32 v[20:21], v[4:5], v[110:111], v[20:21] op_sel:[0,1,0]
	v_pk_fma_f32 v[22:23], v[12:13], v[114:115], v[22:23] op_sel:[0,1,0]
	ds_read_b128 v[68:71], v180 offset:7184
	v_pk_fma_f32 v[20:21], v[6:7], v[112:113], v[20:21] op_sel_hi:[1,0,1]
	v_pk_fma_f32 v[22:23], v[14:15], v[116:117], v[22:23] op_sel_hi:[1,0,1]
	ds_read_b64 v[104:105], v181 offset:23552
	v_pk_fma_f32 v[20:21], v[8:9], v[112:113], v[20:21] op_sel:[0,1,0]
	v_pk_fma_f32 v[22:23], v[16:17], v[116:117], v[22:23] op_sel:[0,1,0]
	ds_read_b128 v[88:91], v180 offset:15360
	ds_read_b128 v[92:95], v180 offset:15376
	v_pk_add_f32 v[20:21], v[20:21], v[22:23]
	ds_read_b128 v[72:75], v180 offset:3072
	ds_read_b128 v[76:79], v180 offset:3088
	v_add_f32_dpp v20, v20, v20 quad_perm:[1,0,3,2] row_mask:0xf bank_mask:0xf bound_ctrl:1
	v_add_f32_dpp v21, v21, v21 quad_perm:[1,0,3,2] row_mask:0xf bank_mask:0xf bound_ctrl:1
	ds_read_b128 v[80:83], v180 offset:11264
	v_add_f32_dpp v20, v20, v20 quad_perm:[2,3,0,1] row_mask:0xf bank_mask:0xf bound_ctrl:1
	v_add_f32_dpp v21, v21, v21 quad_perm:[2,3,0,1] row_mask:0xf bank_mask:0xf bound_ctrl:1
	ds_read_b128 v[84:87], v180 offset:11280
	v_add_f32_dpp v20, v20, v20 row_half_mirror row_mask:0xf bank_mask:0xf bound_ctrl:1
	v_add_f32_dpp v21, v21, v21 row_half_mirror row_mask:0xf bank_mask:0xf bound_ctrl:1
	ds_read_b128 v[96:99], v180 offset:19456
	ds_read_b128 v[100:103], v180 offset:19472
	v_add_f32_dpp v40, v40, v40 quad_perm:[1,0,3,2] row_mask:0xf bank_mask:0xf bound_ctrl:1
	v_add_f32_dpp v41, v41, v41 quad_perm:[1,0,3,2] row_mask:0xf bank_mask:0xf bound_ctrl:1
	v_pk_mul_f32 v[24:25], v[150:151], v[134:135] op_sel_hi:[1,0]
	v_add_f32_dpp v40, v40, v40 quad_perm:[2,3,0,1] row_mask:0xf bank_mask:0xf bound_ctrl:1
	v_add_f32_dpp v41, v41, v41 quad_perm:[2,3,0,1] row_mask:0xf bank_mask:0xf bound_ctrl:1
	v_pk_fma_f32 v[24:25], v[2:3], v[118:119], v[24:25] op_sel_hi:[1,0,1]
	v_add_f32_dpp v40, v40, v40 row_half_mirror row_mask:0xf bank_mask:0xf bound_ctrl:1
	v_add_f32_dpp v41, v41, v41 row_half_mirror row_mask:0xf bank_mask:0xf bound_ctrl:1
	v_pk_fma_f32 v[2:3], v[20:21], v[126:127], v[24:25] op_sel_hi:[1,0,1]
	v_pk_mul_f32 v[26:27], v[150:151], v[134:135] op_sel:[0,1]
	ds_write_b64 v184, v[40:41] offset:31232
	v_pk_mul_f32 v[28:29], v[150:151], v[136:137] op_sel_hi:[1,0]
	v_pk_fma_f32 v[26:27], v[4:5], v[118:119], v[26:27] op_sel:[0,1,0]
	v_pk_mul_f32 v[30:31], v[150:151], v[136:137] op_sel:[0,1]
	v_pk_fma_f32 v[28:29], v[6:7], v[120:121], v[28:29] op_sel_hi:[1,0,1]
	v_pk_fma_f32 v[4:5], v[20:21], v[126:127], v[26:27] op_sel:[0,1,0]
	v_pk_fma_f32 v[30:31], v[8:9], v[120:121], v[30:31] op_sel:[0,1,0]
	v_pk_fma_f32 v[6:7], v[20:21], v[128:129], v[28:29] op_sel_hi:[1,0,1]
	v_pk_mul_f32 v[32:33], v[150:151], v[138:139] op_sel_hi:[1,0]
	v_pk_fma_f32 v[8:9], v[20:21], v[128:129], v[30:31] op_sel:[0,1,0]
	v_pk_mul_f32 v[34:35], v[150:151], v[138:139] op_sel:[0,1]
	v_pk_fma_f32 v[32:33], v[10:11], v[122:123], v[32:33] op_sel_hi:[1,0,1]
	v_pk_mul_f32 v[36:37], v[150:151], v[140:141] op_sel_hi:[1,0]
	v_pk_fma_f32 v[34:35], v[12:13], v[122:123], v[34:35] op_sel:[0,1,0]
	v_pk_fma_f32 v[10:11], v[20:21], v[130:131], v[32:33] op_sel_hi:[1,0,1]
	v_pk_fma_f32 v[36:37], v[14:15], v[124:125], v[36:37] op_sel_hi:[1,0,1]
	v_pk_fma_f32 v[12:13], v[20:21], v[130:131], v[34:35] op_sel:[0,1,0]
	v_pk_mul_f32 v[38:39], v[150:151], v[140:141] op_sel:[0,1]
	v_pk_fma_f32 v[14:15], v[20:21], v[132:133], v[36:37] op_sel_hi:[1,0,1]
	v_pk_mul_f32 v[42:43], v[2:3], v[142:143] op_sel_hi:[1,0]
	v_pk_fma_f32 v[38:39], v[16:17], v[124:125], v[38:39] op_sel:[0,1,0]
	v_pk_mul_f32 v[44:45], v[10:11], v[146:147] op_sel_hi:[1,0]
	v_pk_fma_f32 v[42:43], v[4:5], v[142:143], v[42:43] op_sel:[0,1,0]
	v_pk_fma_f32 v[16:17], v[20:21], v[132:133], v[38:39] op_sel:[0,1,0]
	v_pk_fma_f32 v[44:45], v[12:13], v[146:147], v[44:45] op_sel:[0,1,0]
	v_pk_fma_f32 v[42:43], v[6:7], v[144:145], v[42:43] op_sel_hi:[1,0,1]
	v_pk_fma_f32 v[44:45], v[14:15], v[148:149], v[44:45] op_sel_hi:[1,0,1]
	v_pk_fma_f32 v[42:43], v[8:9], v[144:145], v[42:43] op_sel:[0,1,0]
	v_pk_fma_f32 v[44:45], v[16:17], v[148:149], v[44:45] op_sel:[0,1,0]
	v_pk_add_f32 v[42:43], v[42:43], v[44:45]
	s_waitcnt lgkmcnt(0)
; __device__ __forceinline__ void rwkv_block(KP p, int o, int b, int hd, LAS unsigned char* lds, const bf16_t* P, bf16_t* YB) {
;     ...
;             for (int tt = 0; tt < 16; ++tt) {
;                 const int o8 = tt * 64 + c * 8;
;                 const f32x4 ka = *(const LAS f32x4*)(KK + o8), kb = *(const LAS f32x4*)(KK + o8 + 4);
;                 const f32x4 wa = *(const LAS f32x4*)(Wd + o8), wb = *(const LAS f32x4*)(Wd + o8 + 4);
;                 const f32x4 ba = *(const LAS f32x4*)(BB + o8), bb = *(const LAS f32x4*)(BB + o8 + 4);
;                 const f32x4 ma = *(const LAS f32x4*)(KM + o8), mb = *(const LAS f32x4*)(KM + o8 + 4);
;                 const f32x4 ra = *(const LAS f32x4*)(Rr + o8), rb = *(const LAS f32x4*)(Rr + o8 + 4);
;                 const f32x2 v01 = *(const LAS f32x2*)(Vv + tt * 64 + 2 * rp);
;                 const f32x2 k2[4] = {{ka[0], ka[1]}, {ka[2], ka[3]}, {kb[0], kb[1]}, {kb[2], kb[3]}};
;                 const f32x2 w2[4] = {{wa[0], wa[1]}, {wa[2], wa[3]}, {wb[0], wb[1]}, {wb[2], wb[3]}};
;                 const f32x2 b2[4] = {{ba[0], ba[1]}, {ba[2], ba[3]}, {bb[0], bb[1]}, {bb[2], bb[3]}};
;                 const f32x2 m2[4] = {{ma[0], ma[1]}, {ma[2], ma[3]}, {mb[0], mb[1]}, {mb[2], mb[3]}};
;                 const f32x2 r2[4] = {{ra[0], ra[1]}, {ra[2], ra[3]}, {rb[0], rb[1]}, {rb[2], rb[3]}};
;                 f32x2 accA = s[0][0] * k2[0], accB = s[1][0] * k2[0], accA2 = s[0][2] * k2[2], accB2 = s[1][2] * k2[2];
;                 accA = s[0][1] * k2[1] + accA; accB = s[1][1] * k2[1] + accB; accA2 = s[0][3] * k2[3] + accA2; accB2 = s[1][3] * k2[3] + accB2;
;                 accA = accA + accA2; accB = accB + accB2;
;                 float sa0 = accA.x + accA.y, sa1 = accB.x + accB.y;
;                 sa0 += dpp_f<0xB1>(sa0); sa1 += dpp_f<0xB1>(sa1);
;                 sa0 += dpp_f<0x4E>(sa0); sa1 += dpp_f<0x4E>(sa1);
;                 sa0 += dpp_f<0x141>(sa0); sa1 += dpp_f<0x141>(sa1);
;                 const f32x2 saA = {sa0, sa0}, saB = {sa1, sa1}, vA = {v01.x, v01.x}, vB = {v01.y, v01.y};
;                 f32x2 yA, yB;
; #pragma unroll
;                 for (int j = 0; j < 4; ++j) {
;                     f32x2 tA = vA * m2[j], tB = vB * m2[j];
;                     tA = saA * b2[j] + tA; tB = saB * b2[j] + tB;
;                     s[0][j] = s[0][j] * w2[j] + tA; s[1][j] = s[1][j] * w2[j] + tB;
	v_pk_mul_f32 v[20:21], v[2:3], v[64:65] op_sel_hi:[1,0]
	v_pk_mul_f32 v[22:23], v[10:11], v[68:69] op_sel_hi:[1,0]
	ds_read_b128 v[110:113], v180 offset:7424
	v_pk_fma_f32 v[20:21], v[4:5], v[64:65], v[20:21] op_sel:[0,1,0]
	v_pk_fma_f32 v[22:23], v[12:13], v[68:69], v[22:23] op_sel:[0,1,0]
	ds_read_b128 v[114:117], v180 offset:7440
	v_pk_fma_f32 v[20:21], v[6:7], v[66:67], v[20:21] op_sel_hi:[1,0,1]
	v_pk_fma_f32 v[22:23], v[14:15], v[70:71], v[22:23] op_sel_hi:[1,0,1]
	ds_read_b64 v[150:151], v181 offset:23808
	v_pk_fma_f32 v[20:21], v[8:9], v[66:67], v[20:21] op_sel:[0,1,0]
	v_pk_fma_f32 v[22:23], v[16:17], v[70:71], v[22:23] op_sel:[0,1,0]
	ds_read_b128 v[134:137], v180 offset:15616
	ds_read_b128 v[138:141], v180 offset:15632
	v_pk_add_f32 v[20:21], v[20:21], v[22:23]
	ds_read_b128 v[118:121], v180 offset:3328
	ds_read_b128 v[122:125], v180 offset:3344
	v_add_f32_dpp v20, v20, v20 quad_perm:[1,0,3,2] row_mask:0xf bank_mask:0xf bound_ctrl:1
	v_add_f32_dpp v21, v21, v21 quad_perm:[1,0,3,2] row_mask:0xf bank_mask:0xf bound_ctrl:1
	ds_read_b128 v[126:129], v180 offset:11520
	v_add_f32_dpp v20, v20, v20 quad_perm:[2,3,0,1] row_mask:0xf bank_mask:0xf bound_ctrl:1
	v_add_f32_dpp v21, v21, v21 quad_perm:[2,3,0,1] row_mask:0xf bank_mask:0xf bound_ctrl:1
	ds_read_b128 v[130:133], v180 offset:11536
	v_add_f32_dpp v20, v20, v20 row_half_mirror row_mask:0xf bank_mask:0xf bound_ctrl:1
	v_add_f32_dpp v21, v21, v21 row_half_mirror row_mask:0xf bank_mask:0xf bound_ctrl:1
	ds_read_b128 v[142:145], v180 offset:19712
	ds_read_b128 v[146:149], v180 offset:19728
	v_add_f32_dpp v42, v42, v42 quad_perm:[1,0,3,2] row_mask:0xf bank_mask:0xf bound_ctrl:1
	v_add_f32_dpp v43, v43, v43 quad_perm:[1,0,3,2] row_mask:0xf bank_mask:0xf bound_ctrl:1
	v_pk_mul_f32 v[24:25], v[104:105], v[88:89] op_sel_hi:[1,0]
	v_add_f32_dpp v42, v42, v42 quad_perm:[2,3,0,1] row_mask:0xf bank_mask:0xf bound_ctrl:1
	v_add_f32_dpp v43, v43, v43 quad_perm:[2,3,0,1] row_mask:0xf bank_mask:0xf bound_ctrl:1
	v_pk_fma_f32 v[24:25], v[2:3], v[72:73], v[24:25] op_sel_hi:[1,0,1]
	v_add_f32_dpp v42, v42, v42 row_half_mirror row_mask:0xf bank_mask:0xf bound_ctrl:1
	v_add_f32_dpp v43, v43, v43 row_half_mirror row_mask:0xf bank_mask:0xf bound_ctrl:1
	v_pk_fma_f32 v[2:3], v[20:21], v[80:81], v[24:25] op_sel_hi:[1,0,1]
	v_pk_mul_f32 v[26:27], v[104:105], v[88:89] op_sel:[0,1]
	ds_write_b64 v184, v[42:43] offset:31488
	v_pk_mul_f32 v[28:29], v[104:105], v[90:91] op_sel_hi:[1,0]
	v_pk_fma_f32 v[26:27], v[4:5], v[72:73], v[26:27] op_sel:[0,1,0]
	v_pk_mul_f32 v[30:31], v[104:105], v[90:91] op_sel:[0,1]
	v_pk_fma_f32 v[28:29], v[6:7], v[74:75], v[28:29] op_sel_hi:[1,0,1]
	v_pk_fma_f32 v[4:5], v[20:21], v[80:81], v[26:27] op_sel:[0,1,0]
	v_pk_fma_f32 v[30:31], v[8:9], v[74:75], v[30:31] op_sel:[0,1,0]
	v_pk_fma_f32 v[6:7], v[20:21], v[82:83], v[28:29] op_sel_hi:[1,0,1]
	v_pk_mul_f32 v[32:33], v[104:105], v[92:93] op_sel_hi:[1,0]
	v_pk_fma_f32 v[8:9], v[20:21], v[82:83], v[30:31] op_sel:[0,1,0]
	v_pk_mul_f32 v[34:35], v[104:105], v[92:93] op_sel:[0,1]
	v_pk_fma_f32 v[32:33], v[10:11], v[76:77], v[32:33] op_sel_hi:[1,0,1]
	v_pk_mul_f32 v[36:37], v[104:105], v[94:95] op_sel_hi:[1,0]
	v_pk_fma_f32 v[34:35], v[12:13], v[76:77], v[34:35] op_sel:[0,1,0]
	v_pk_fma_f32 v[10:11], v[20:21], v[84:85], v[32:33] op_sel_hi:[1,0,1]
	v_pk_fma_f32 v[36:37], v[14:15], v[78:79], v[36:37] op_sel_hi:[1,0,1]
	v_pk_fma_f32 v[12:13], v[20:21], v[84:85], v[34:35] op_sel:[0,1,0]
	v_pk_mul_f32 v[38:39], v[104:105], v[94:95] op_sel:[0,1]
	v_pk_fma_f32 v[14:15], v[20:21], v[86:87], v[36:37] op_sel_hi:[1,0,1]
	v_pk_mul_f32 v[40:41], v[2:3], v[96:97] op_sel_hi:[1,0]
	v_pk_fma_f32 v[38:39], v[16:17], v[78:79], v[38:39] op_sel:[0,1,0]
	v_pk_mul_f32 v[44:45], v[10:11], v[100:101] op_sel_hi:[1,0]
	v_pk_fma_f32 v[40:41], v[4:5], v[96:97], v[40:41] op_sel:[0,1,0]
	v_pk_fma_f32 v[16:17], v[20:21], v[86:87], v[38:39] op_sel:[0,1,0]
	v_pk_fma_f32 v[44:45], v[12:13], v[100:101], v[44:45] op_sel:[0,1,0]
	v_pk_fma_f32 v[40:41], v[6:7], v[98:99], v[40:41] op_sel_hi:[1,0,1]
	v_pk_fma_f32 v[44:45], v[14:15], v[102:103], v[44:45] op_sel_hi:[1,0,1]
	v_pk_fma_f32 v[40:41], v[8:9], v[98:99], v[40:41] op_sel:[0,1,0]
	v_pk_fma_f32 v[44:45], v[16:17], v[102:103], v[44:45] op_sel:[0,1,0]
	v_pk_add_f32 v[40:41], v[40:41], v[44:45]
	s_waitcnt lgkmcnt(0)
; __device__ __forceinline__ void rwkv_block(KP p, int o, int b, int hd, LAS unsigned char* lds, const bf16_t* P, bf16_t* YB) {
;     ...
;             for (int tt = 0; tt < 16; ++tt) {
;                 const int o8 = tt * 64 + c * 8;
;                 const f32x4 ka = *(const LAS f32x4*)(KK + o8), kb = *(const LAS f32x4*)(KK + o8 + 4);
;                 const f32x4 wa = *(const LAS f32x4*)(Wd + o8), wb = *(const LAS f32x4*)(Wd + o8 + 4);
;                 const f32x4 ba = *(const LAS f32x4*)(BB + o8), bb = *(const LAS f32x4*)(BB + o8 + 4);
;                 const f32x4 ma = *(const LAS f32x4*)(KM + o8), mb = *(const LAS f32x4*)(KM + o8 + 4);
;                 const f32x4 ra = *(const LAS f32x4*)(Rr + o8), rb = *(const LAS f32x4*)(Rr + o8 + 4);
;                 const f32x2 v01 = *(const LAS f32x2*)(Vv + tt * 64 + 2 * rp);
;                 const f32x2 k2[4] = {{ka[0], ka[1]}, {ka[2], ka[3]}, {kb[0], kb[1]}, {kb[2], kb[3]}};
;                 const f32x2 w2[4] = {{wa[0], wa[1]}, {wa[2], wa[3]}, {wb[0], wb[1]}, {wb[2], wb[3]}};
;                 const f32x2 b2[4] = {{ba[0], ba[1]}, {ba[2], ba[3]}, {bb[0], bb[1]}, {bb[2], bb[3]}};
;                 const f32x2 m2[4] = {{ma[0], ma[1]}, {ma[2], ma[3]}, {mb[0], mb[1]}, {mb[2], mb[3]}};
;                 const f32x2 r2[4] = {{ra[0], ra[1]}, {ra[2], ra[3]}, {rb[0], rb[1]}, {rb[2], rb[3]}};
;                 f32x2 accA = s[0][0] * k2[0], accB = s[1][0] * k2[0], accA2 = s[0][2] * k2[2], accB2 = s[1][2] * k2[2];
;                 accA = s[0][1] * k2[1] + accA; accB = s[1][1] * k2[1] + accB; accA2 = s[0][3] * k2[3] + accA2; accB2 = s[1][3] * k2[3] + accB2;
;                 accA = accA + accA2; accB = accB + accB2;
;                 float sa0 = accA.x + accA.y, sa1 = accB.x + accB.y;
;                 sa0 += dpp_f<0xB1>(sa0); sa1 += dpp_f<0xB1>(sa1);
;                 sa0 += dpp_f<0x4E>(sa0); sa1 += dpp_f<0x4E>(sa1);
;                 sa0 += dpp_f<0x141>(sa0); sa1 += dpp_f<0x141>(sa1);
;                 const f32x2 saA = {sa0, sa0}, saB = {sa1, sa1}, vA = {v01.x, v01.x}, vB = {v01.y, v01.y};
;                 f32x2 yA, yB;
; #pragma unroll
;                 for (int j = 0; j < 4; ++j) {
;                     f32x2 tA = vA * m2[j], tB = vB * m2[j];
;                     tA = saA * b2[j] + tA; tB = saB * b2[j] + tB;
;                     s[0][j] = s[0][j] * w2[j] + tA; s[1][j] = s[1][j] * w2[j] + tB;
	v_pk_mul_f32 v[20:21], v[2:3], v[110:111] op_sel_hi:[1,0]
	v_pk_mul_f32 v[22:23], v[10:11], v[114:115] op_sel_hi:[1,0]
	ds_read_b128 v[64:67], v180 offset:7680
	v_pk_fma_f32 v[20:21], v[4:5], v[110:111], v[20:21] op_sel:[0,1,0]
	v_pk_fma_f32 v[22:23], v[12:13], v[114:115], v[22:23] op_sel:[0,1,0]
	ds_read_b128 v[68:71], v180 offset:7696
	v_pk_fma_f32 v[20:21], v[6:7], v[112:113], v[20:21] op_sel_hi:[1,0,1]
	v_pk_fma_f32 v[22:23], v[14:15], v[116:117], v[22:23] op_sel_hi:[1,0,1]
	ds_read_b64 v[104:105], v181 offset:24064
	v_pk_fma_f32 v[20:21], v[8:9], v[112:113], v[20:21] op_sel:[0,1,0]
	v_pk_fma_f32 v[22:23], v[16:17], v[116:117], v[22:23] op_sel:[0,1,0]
	ds_read_b128 v[88:91], v180 offset:15872
	ds_read_b128 v[92:95], v180 offset:15888
	v_pk_add_f32 v[20:21], v[20:21], v[22:23]
	ds_read_b128 v[72:75], v180 offset:3584
	ds_read_b128 v[76:79], v180 offset:3600
	v_add_f32_dpp v20, v20, v20 quad_perm:[1,0,3,2] row_mask:0xf bank_mask:0xf bound_ctrl:1
	v_add_f32_dpp v21, v21, v21 quad_perm:[1,0,3,2] row_mask:0xf bank_mask:0xf bound_ctrl:1
	ds_read_b128 v[80:83], v180 offset:11776
	v_add_f32_dpp v20, v20, v20 quad_perm:[2,3,0,1] row_mask:0xf bank_mask:0xf bound_ctrl:1
	v_add_f32_dpp v21, v21, v21 quad_perm:[2,3,0,1] row_mask:0xf bank_mask:0xf bound_ctrl:1
	ds_read_b128 v[84:87], v180 offset:11792
	v_add_f32_dpp v20, v20, v20 row_half_mirror row_mask:0xf bank_mask:0xf bound_ctrl:1
	v_add_f32_dpp v21, v21, v21 row_half_mirror row_mask:0xf bank_mask:0xf bound_ctrl:1
	ds_read_b128 v[96:99], v180 offset:19968
	ds_read_b128 v[100:103], v180 offset:19984
	v_add_f32_dpp v40, v40, v40 quad_perm:[1,0,3,2] row_mask:0xf bank_mask:0xf bound_ctrl:1
	v_add_f32_dpp v41, v41, v41 quad_perm:[1,0,3,2] row_mask:0xf bank_mask:0xf bound_ctrl:1
	v_pk_mul_f32 v[24:25], v[150:151], v[134:135] op_sel_hi:[1,0]
	v_add_f32_dpp v40, v40, v40 quad_perm:[2,3,0,1] row_mask:0xf bank_mask:0xf bound_ctrl:1
	v_add_f32_dpp v41, v41, v41 quad_perm:[2,3,0,1] row_mask:0xf bank_mask:0xf bound_ctrl:1
	v_pk_fma_f32 v[24:25], v[2:3], v[118:119], v[24:25] op_sel_hi:[1,0,1]
	v_add_f32_dpp v40, v40, v40 row_half_mirror row_mask:0xf bank_mask:0xf bound_ctrl:1
	v_add_f32_dpp v41, v41, v41 row_half_mirror row_mask:0xf bank_mask:0xf bound_ctrl:1
	v_pk_fma_f32 v[2:3], v[20:21], v[126:127], v[24:25] op_sel_hi:[1,0,1]
	v_pk_mul_f32 v[26:27], v[150:151], v[134:135] op_sel:[0,1]
	ds_write_b64 v184, v[40:41] offset:31744
	v_pk_mul_f32 v[28:29], v[150:151], v[136:137] op_sel_hi:[1,0]
	v_pk_fma_f32 v[26:27], v[4:5], v[118:119], v[26:27] op_sel:[0,1,0]
	v_pk_mul_f32 v[30:31], v[150:151], v[136:137] op_sel:[0,1]
	v_pk_fma_f32 v[28:29], v[6:7], v[120:121], v[28:29] op_sel_hi:[1,0,1]
	v_pk_fma_f32 v[4:5], v[20:21], v[126:127], v[26:27] op_sel:[0,1,0]
	v_pk_fma_f32 v[30:31], v[8:9], v[120:121], v[30:31] op_sel:[0,1,0]
	v_pk_fma_f32 v[6:7], v[20:21], v[128:129], v[28:29] op_sel_hi:[1,0,1]
	v_pk_mul_f32 v[32:33], v[150:151], v[138:139] op_sel_hi:[1,0]
	v_pk_fma_f32 v[8:9], v[20:21], v[128:129], v[30:31] op_sel:[0,1,0]
	v_pk_mul_f32 v[34:35], v[150:151], v[138:139] op_sel:[0,1]
	v_pk_fma_f32 v[32:33], v[10:11], v[122:123], v[32:33] op_sel_hi:[1,0,1]
	v_pk_mul_f32 v[36:37], v[150:151], v[140:141] op_sel_hi:[1,0]
	v_pk_fma_f32 v[34:35], v[12:13], v[122:123], v[34:35] op_sel:[0,1,0]
	v_pk_fma_f32 v[10:11], v[20:21], v[130:131], v[32:33] op_sel_hi:[1,0,1]
	v_pk_fma_f32 v[36:37], v[14:15], v[124:125], v[36:37] op_sel_hi:[1,0,1]
	v_pk_fma_f32 v[12:13], v[20:21], v[130:131], v[34:35] op_sel:[0,1,0]
	v_pk_mul_f32 v[38:39], v[150:151], v[140:141] op_sel:[0,1]
	v_pk_fma_f32 v[14:15], v[20:21], v[132:133], v[36:37] op_sel_hi:[1,0,1]
	v_pk_mul_f32 v[42:43], v[2:3], v[142:143] op_sel_hi:[1,0]
	v_pk_fma_f32 v[38:39], v[16:17], v[124:125], v[38:39] op_sel:[0,1,0]
	v_pk_mul_f32 v[44:45], v[10:11], v[146:147] op_sel_hi:[1,0]
	v_pk_fma_f32 v[42:43], v[4:5], v[142:143], v[42:43] op_sel:[0,1,0]
	v_pk_fma_f32 v[16:17], v[20:21], v[132:133], v[38:39] op_sel:[0,1,0]
	v_pk_fma_f32 v[44:45], v[12:13], v[146:147], v[44:45] op_sel:[0,1,0]
	v_pk_fma_f32 v[42:43], v[6:7], v[144:145], v[42:43] op_sel_hi:[1,0,1]
	v_pk_fma_f32 v[44:45], v[14:15], v[148:149], v[44:45] op_sel_hi:[1,0,1]
	v_pk_fma_f32 v[42:43], v[8:9], v[144:145], v[42:43] op_sel:[0,1,0]
	v_pk_fma_f32 v[44:45], v[16:17], v[148:149], v[44:45] op_sel:[0,1,0]
	v_pk_add_f32 v[42:43], v[42:43], v[44:45]
	s_waitcnt lgkmcnt(0)
; __device__ __forceinline__ void rwkv_block(KP p, int o, int b, int hd, LAS unsigned char* lds, const bf16_t* P, bf16_t* YB) {
;     ...
;             for (int tt = 0; tt < 16; ++tt) {
;                 const int o8 = tt * 64 + c * 8;
;                 const f32x4 ka = *(const LAS f32x4*)(KK + o8), kb = *(const LAS f32x4*)(KK + o8 + 4);
;                 const f32x4 wa = *(const LAS f32x4*)(Wd + o8), wb = *(const LAS f32x4*)(Wd + o8 + 4);
;                 const f32x4 ba = *(const LAS f32x4*)(BB + o8), bb = *(const LAS f32x4*)(BB + o8 + 4);
;                 const f32x4 ma = *(const LAS f32x4*)(KM + o8), mb = *(const LAS f32x4*)(KM + o8 + 4);
;                 const f32x4 ra = *(const LAS f32x4*)(Rr + o8), rb = *(const LAS f32x4*)(Rr + o8 + 4);
;                 const f32x2 v01 = *(const LAS f32x2*)(Vv + tt * 64 + 2 * rp);
;                 const f32x2 k2[4] = {{ka[0], ka[1]}, {ka[2], ka[3]}, {kb[0], kb[1]}, {kb[2], kb[3]}};
;                 const f32x2 w2[4] = {{wa[0], wa[1]}, {wa[2], wa[3]}, {wb[0], wb[1]}, {wb[2], wb[3]}};
;                 const f32x2 b2[4] = {{ba[0], ba[1]}, {ba[2], ba[3]}, {bb[0], bb[1]}, {bb[2], bb[3]}};
;                 const f32x2 m2[4] = {{ma[0], ma[1]}, {ma[2], ma[3]}, {mb[0], mb[1]}, {mb[2], mb[3]}};
;                 const f32x2 r2[4] = {{ra[0], ra[1]}, {ra[2], ra[3]}, {rb[0], rb[1]}, {rb[2], rb[3]}};
;                 f32x2 accA = s[0][0] * k2[0], accB = s[1][0] * k2[0], accA2 = s[0][2] * k2[2], accB2 = s[1][2] * k2[2];
;                 accA = s[0][1] * k2[1] + accA; accB = s[1][1] * k2[1] + accB; accA2 = s[0][3] * k2[3] + accA2; accB2 = s[1][3] * k2[3] + accB2;
;                 accA = accA + accA2; accB = accB + accB2;
;                 float sa0 = accA.x + accA.y, sa1 = accB.x + accB.y;
;                 sa0 += dpp_f<0xB1>(sa0); sa1 += dpp_f<0xB1>(sa1);
;                 sa0 += dpp_f<0x4E>(sa0); sa1 += dpp_f<0x4E>(sa1);
;                 sa0 += dpp_f<0x141>(sa0); sa1 += dpp_f<0x141>(sa1);
;                 const f32x2 saA = {sa0, sa0}, saB = {sa1, sa1}, vA = {v01.x, v01.x}, vB = {v01.y, v01.y};
;                 f32x2 yA, yB;
; #pragma unroll
;                 for (int j = 0; j < 4; ++j) {
;                     f32x2 tA = vA * m2[j], tB = vB * m2[j];
;                     tA = saA * b2[j] + tA; tB = saB * b2[j] + tB;
;                     s[0][j] = s[0][j] * w2[j] + tA; s[1][j] = s[1][j] * w2[j] + tB;
	v_pk_mul_f32 v[20:21], v[2:3], v[64:65] op_sel_hi:[1,0]
	v_pk_mul_f32 v[22:23], v[10:11], v[68:69] op_sel_hi:[1,0]
	ds_read_b128 v[110:113], v180 offset:7936
	v_pk_fma_f32 v[20:21], v[4:5], v[64:65], v[20:21] op_sel:[0,1,0]
	v_pk_fma_f32 v[22:23], v[12:13], v[68:69], v[22:23] op_sel:[0,1,0]
	ds_read_b128 v[114:117], v180 offset:7952
	v_pk_fma_f32 v[20:21], v[6:7], v[66:67], v[20:21] op_sel_hi:[1,0,1]
	v_pk_fma_f32 v[22:23], v[14:15], v[70:71], v[22:23] op_sel_hi:[1,0,1]
	ds_read_b64 v[150:151], v181 offset:24320
	v_pk_fma_f32 v[20:21], v[8:9], v[66:67], v[20:21] op_sel:[0,1,0]
	v_pk_fma_f32 v[22:23], v[16:17], v[70:71], v[22:23] op_sel:[0,1,0]
	ds_read_b128 v[134:137], v180 offset:16128
	ds_read_b128 v[138:141], v180 offset:16144
	v_pk_add_f32 v[20:21], v[20:21], v[22:23]
	ds_read_b128 v[118:121], v180 offset:3840
	ds_read_b128 v[122:125], v180 offset:3856
	v_add_f32_dpp v20, v20, v20 quad_perm:[1,0,3,2] row_mask:0xf bank_mask:0xf bound_ctrl:1
	v_add_f32_dpp v21, v21, v21 quad_perm:[1,0,3,2] row_mask:0xf bank_mask:0xf bound_ctrl:1
	ds_read_b128 v[126:129], v180 offset:12032
	v_add_f32_dpp v20, v20, v20 quad_perm:[2,3,0,1] row_mask:0xf bank_mask:0xf bound_ctrl:1
	v_add_f32_dpp v21, v21, v21 quad_perm:[2,3,0,1] row_mask:0xf bank_mask:0xf bound_ctrl:1
	ds_read_b128 v[130:133], v180 offset:12048
	v_add_f32_dpp v20, v20, v20 row_half_mirror row_mask:0xf bank_mask:0xf bound_ctrl:1
	v_add_f32_dpp v21, v21, v21 row_half_mirror row_mask:0xf bank_mask:0xf bound_ctrl:1
	ds_read_b128 v[142:145], v180 offset:20224
	ds_read_b128 v[146:149], v180 offset:20240
	v_add_f32_dpp v42, v42, v42 quad_perm:[1,0,3,2] row_mask:0xf bank_mask:0xf bound_ctrl:1
	v_add_f32_dpp v43, v43, v43 quad_perm:[1,0,3,2] row_mask:0xf bank_mask:0xf bound_ctrl:1
	v_pk_mul_f32 v[24:25], v[104:105], v[88:89] op_sel_hi:[1,0]
	v_add_f32_dpp v42, v42, v42 quad_perm:[2,3,0,1] row_mask:0xf bank_mask:0xf bound_ctrl:1
	v_add_f32_dpp v43, v43, v43 quad_perm:[2,3,0,1] row_mask:0xf bank_mask:0xf bound_ctrl:1
	v_pk_fma_f32 v[24:25], v[2:3], v[72:73], v[24:25] op_sel_hi:[1,0,1]
	v_add_f32_dpp v42, v42, v42 row_half_mirror row_mask:0xf bank_mask:0xf bound_ctrl:1
	v_add_f32_dpp v43, v43, v43 row_half_mirror row_mask:0xf bank_mask:0xf bound_ctrl:1
	v_pk_fma_f32 v[2:3], v[20:21], v[80:81], v[24:25] op_sel_hi:[1,0,1]
	v_pk_mul_f32 v[26:27], v[104:105], v[88:89] op_sel:[0,1]
	ds_write_b64 v184, v[42:43] offset:32000
	v_pk_mul_f32 v[28:29], v[104:105], v[90:91] op_sel_hi:[1,0]
	v_pk_fma_f32 v[26:27], v[4:5], v[72:73], v[26:27] op_sel:[0,1,0]
	v_pk_mul_f32 v[30:31], v[104:105], v[90:91] op_sel:[0,1]
	v_pk_fma_f32 v[28:29], v[6:7], v[74:75], v[28:29] op_sel_hi:[1,0,1]
	v_pk_fma_f32 v[4:5], v[20:21], v[80:81], v[26:27] op_sel:[0,1,0]
	v_pk_fma_f32 v[30:31], v[8:9], v[74:75], v[30:31] op_sel:[0,1,0]
	v_pk_fma_f32 v[6:7], v[20:21], v[82:83], v[28:29] op_sel_hi:[1,0,1]
	v_pk_mul_f32 v[32:33], v[104:105], v[92:93] op_sel_hi:[1,0]
	v_pk_fma_f32 v[8:9], v[20:21], v[82:83], v[30:31] op_sel:[0,1,0]
	v_pk_mul_f32 v[34:35], v[104:105], v[92:93] op_sel:[0,1]
	v_pk_fma_f32 v[32:33], v[10:11], v[76:77], v[32:33] op_sel_hi:[1,0,1]
	v_pk_mul_f32 v[36:37], v[104:105], v[94:95] op_sel_hi:[1,0]
	v_pk_fma_f32 v[34:35], v[12:13], v[76:77], v[34:35] op_sel:[0,1,0]
	v_pk_fma_f32 v[10:11], v[20:21], v[84:85], v[32:33] op_sel_hi:[1,0,1]
	v_pk_fma_f32 v[36:37], v[14:15], v[78:79], v[36:37] op_sel_hi:[1,0,1]
	v_pk_fma_f32 v[12:13], v[20:21], v[84:85], v[34:35] op_sel:[0,1,0]
	v_pk_mul_f32 v[38:39], v[104:105], v[94:95] op_sel:[0,1]
	v_pk_fma_f32 v[14:15], v[20:21], v[86:87], v[36:37] op_sel_hi:[1,0,1]
	v_pk_mul_f32 v[40:41], v[2:3], v[96:97] op_sel_hi:[1,0]
	v_pk_fma_f32 v[38:39], v[16:17], v[78:79], v[38:39] op_sel:[0,1,0]
	v_pk_mul_f32 v[44:45], v[10:11], v[100:101] op_sel_hi:[1,0]
	v_pk_fma_f32 v[40:41], v[4:5], v[96:97], v[40:41] op_sel:[0,1,0]
	v_pk_fma_f32 v[16:17], v[20:21], v[86:87], v[38:39] op_sel:[0,1,0]
	v_pk_fma_f32 v[44:45], v[12:13], v[100:101], v[44:45] op_sel:[0,1,0]
	v_pk_fma_f32 v[40:41], v[6:7], v[98:99], v[40:41] op_sel_hi:[1,0,1]
	v_pk_fma_f32 v[44:45], v[14:15], v[102:103], v[44:45] op_sel_hi:[1,0,1]
	v_pk_fma_f32 v[40:41], v[8:9], v[98:99], v[40:41] op_sel:[0,1,0]
	v_pk_fma_f32 v[44:45], v[16:17], v[102:103], v[44:45] op_sel:[0,1,0]
	v_pk_add_f32 v[40:41], v[40:41], v[44:45]
	s_waitcnt lgkmcnt(0)
	s_barrier
; __device__ __forceinline__ void rwkv_block(KP p, int o, int b, int hd, LAS unsigned char* lds, const bf16_t* P, bf16_t* YB) {
;     ...
;             for (int tt = 0; tt < 16; ++tt) {
;                 const int o8 = tt * 64 + c * 8;
;                 const f32x4 ka = *(const LAS f32x4*)(KK + o8), kb = *(const LAS f32x4*)(KK + o8 + 4);
;                 const f32x4 wa = *(const LAS f32x4*)(Wd + o8), wb = *(const LAS f32x4*)(Wd + o8 + 4);
;                 const f32x4 ba = *(const LAS f32x4*)(BB + o8), bb = *(const LAS f32x4*)(BB + o8 + 4);
;                 const f32x4 ma = *(const LAS f32x4*)(KM + o8), mb = *(const LAS f32x4*)(KM + o8 + 4);
;                 const f32x4 ra = *(const LAS f32x4*)(Rr + o8), rb = *(const LAS f32x4*)(Rr + o8 + 4);
;                 const f32x2 v01 = *(const LAS f32x2*)(Vv + tt * 64 + 2 * rp);
;                 const f32x2 k2[4] = {{ka[0], ka[1]}, {ka[2], ka[3]}, {kb[0], kb[1]}, {kb[2], kb[3]}};
;                 const f32x2 w2[4] = {{wa[0], wa[1]}, {wa[2], wa[3]}, {wb[0], wb[1]}, {wb[2], wb[3]}};
;                 const f32x2 b2[4] = {{ba[0], ba[1]}, {ba[2], ba[3]}, {bb[0], bb[1]}, {bb[2], bb[3]}};
;                 const f32x2 m2[4] = {{ma[0], ma[1]}, {ma[2], ma[3]}, {mb[0], mb[1]}, {mb[2], mb[3]}};
;                 const f32x2 r2[4] = {{ra[0], ra[1]}, {ra[2], ra[3]}, {rb[0], rb[1]}, {rb[2], rb[3]}};
;                 f32x2 accA = s[0][0] * k2[0], accB = s[1][0] * k2[0], accA2 = s[0][2] * k2[2], accB2 = s[1][2] * k2[2];
;                 accA = s[0][1] * k2[1] + accA; accB = s[1][1] * k2[1] + accB; accA2 = s[0][3] * k2[3] + accA2; accB2 = s[1][3] * k2[3] + accB2;
;                 accA = accA + accA2; accB = accB + accB2;
;                 float sa0 = accA.x + accA.y, sa1 = accB.x + accB.y;
;                 sa0 += dpp_f<0xB1>(sa0); sa1 += dpp_f<0xB1>(sa1);
;                 sa0 += dpp_f<0x4E>(sa0); sa1 += dpp_f<0x4E>(sa1);
;                 sa0 += dpp_f<0x141>(sa0); sa1 += dpp_f<0x141>(sa1);
;                 const f32x2 saA = {sa0, sa0}, saB = {sa1, sa1}, vA = {v01.x, v01.x}, vB = {v01.y, v01.y};
;                 f32x2 yA, yB;
; #pragma unroll
;                 for (int j = 0; j < 4; ++j) {
;                     f32x2 tA = vA * m2[j], tB = vB * m2[j];
;                     tA = saA * b2[j] + tA; tB = saB * b2[j] + tB;
;                     s[0][j] = s[0][j] * w2[j] + tA; s[1][j] = s[1][j] * w2[j] + tB;
	v_pk_mul_f32 v[20:21], v[2:3], v[110:111] op_sel_hi:[1,0]
	v_pk_mul_f32 v[22:23], v[10:11], v[114:115] op_sel_hi:[1,0]
	ds_read_b128 v[64:67], v186 offset:4096
	v_pk_fma_f32 v[20:21], v[4:5], v[110:111], v[20:21] op_sel:[0,1,0]
	v_pk_fma_f32 v[22:23], v[12:13], v[114:115], v[22:23] op_sel:[0,1,0]
	ds_read_b128 v[68:71], v186 offset:4112
	v_pk_fma_f32 v[20:21], v[6:7], v[112:113], v[20:21] op_sel_hi:[1,0,1]
	v_pk_fma_f32 v[22:23], v[14:15], v[116:117], v[22:23] op_sel_hi:[1,0,1]
	ds_read_b64 v[104:105], v187 offset:20480
	v_pk_fma_f32 v[20:21], v[8:9], v[112:113], v[20:21] op_sel:[0,1,0]
	v_pk_fma_f32 v[22:23], v[16:17], v[116:117], v[22:23] op_sel:[0,1,0]
	ds_read_b128 v[88:91], v186 offset:12288
	ds_read_b128 v[92:95], v186 offset:12304
	v_pk_add_f32 v[20:21], v[20:21], v[22:23]
	ds_read_b128 v[72:75], v186 offset:0
	ds_read_b128 v[76:79], v186 offset:16
	v_add_f32_dpp v20, v20, v20 quad_perm:[1,0,3,2] row_mask:0xf bank_mask:0xf bound_ctrl:1
	v_add_f32_dpp v21, v21, v21 quad_perm:[1,0,3,2] row_mask:0xf bank_mask:0xf bound_ctrl:1
	ds_read_b128 v[80:83], v186 offset:8192
	v_add_f32_dpp v20, v20, v20 quad_perm:[2,3,0,1] row_mask:0xf bank_mask:0xf bound_ctrl:1
	v_add_f32_dpp v21, v21, v21 quad_perm:[2,3,0,1] row_mask:0xf bank_mask:0xf bound_ctrl:1
	ds_read_b128 v[84:87], v186 offset:8208
	v_add_f32_dpp v20, v20, v20 row_half_mirror row_mask:0xf bank_mask:0xf bound_ctrl:1
	v_add_f32_dpp v21, v21, v21 row_half_mirror row_mask:0xf bank_mask:0xf bound_ctrl:1
	ds_read_b128 v[96:99], v186 offset:16384
	ds_read_b128 v[100:103], v186 offset:16400
	v_add_f32_dpp v40, v40, v40 quad_perm:[1,0,3,2] row_mask:0xf bank_mask:0xf bound_ctrl:1
	v_add_f32_dpp v41, v41, v41 quad_perm:[1,0,3,2] row_mask:0xf bank_mask:0xf bound_ctrl:1
	v_pk_mul_f32 v[24:25], v[150:151], v[134:135] op_sel_hi:[1,0]
	v_add_f32_dpp v40, v40, v40 quad_perm:[2,3,0,1] row_mask:0xf bank_mask:0xf bound_ctrl:1
	v_add_f32_dpp v41, v41, v41 quad_perm:[2,3,0,1] row_mask:0xf bank_mask:0xf bound_ctrl:1
	v_pk_fma_f32 v[24:25], v[2:3], v[118:119], v[24:25] op_sel_hi:[1,0,1]
	v_add_f32_dpp v40, v40, v40 row_half_mirror row_mask:0xf bank_mask:0xf bound_ctrl:1
	v_add_f32_dpp v41, v41, v41 row_half_mirror row_mask:0xf bank_mask:0xf bound_ctrl:1
	v_pk_fma_f32 v[2:3], v[20:21], v[126:127], v[24:25] op_sel_hi:[1,0,1]
	v_pk_mul_f32 v[26:27], v[150:151], v[134:135] op_sel:[0,1]
	ds_write_b64 v184, v[40:41] offset:32256
	v_pk_mul_f32 v[28:29], v[150:151], v[136:137] op_sel_hi:[1,0]
	v_pk_fma_f32 v[26:27], v[4:5], v[118:119], v[26:27] op_sel:[0,1,0]
	v_pk_mul_f32 v[30:31], v[150:151], v[136:137] op_sel:[0,1]
	v_pk_fma_f32 v[28:29], v[6:7], v[120:121], v[28:29] op_sel_hi:[1,0,1]
	v_pk_fma_f32 v[4:5], v[20:21], v[126:127], v[26:27] op_sel:[0,1,0]
	v_pk_fma_f32 v[30:31], v[8:9], v[120:121], v[30:31] op_sel:[0,1,0]
	v_pk_fma_f32 v[6:7], v[20:21], v[128:129], v[28:29] op_sel_hi:[1,0,1]
	v_pk_mul_f32 v[32:33], v[150:151], v[138:139] op_sel_hi:[1,0]
	v_pk_fma_f32 v[8:9], v[20:21], v[128:129], v[30:31] op_sel:[0,1,0]
	v_pk_mul_f32 v[34:35], v[150:151], v[138:139] op_sel:[0,1]
	v_pk_fma_f32 v[32:33], v[10:11], v[122:123], v[32:33] op_sel_hi:[1,0,1]
	v_pk_mul_f32 v[36:37], v[150:151], v[140:141] op_sel_hi:[1,0]
	v_pk_fma_f32 v[34:35], v[12:13], v[122:123], v[34:35] op_sel:[0,1,0]
	v_pk_fma_f32 v[10:11], v[20:21], v[130:131], v[32:33] op_sel_hi:[1,0,1]
	v_pk_fma_f32 v[36:37], v[14:15], v[124:125], v[36:37] op_sel_hi:[1,0,1]
	v_pk_fma_f32 v[12:13], v[20:21], v[130:131], v[34:35] op_sel:[0,1,0]
	v_pk_mul_f32 v[38:39], v[150:151], v[140:141] op_sel:[0,1]
	v_pk_fma_f32 v[14:15], v[20:21], v[132:133], v[36:37] op_sel_hi:[1,0,1]
	v_pk_mul_f32 v[42:43], v[2:3], v[142:143] op_sel_hi:[1,0]
	v_pk_fma_f32 v[38:39], v[16:17], v[124:125], v[38:39] op_sel:[0,1,0]
	v_pk_mul_f32 v[44:45], v[10:11], v[146:147] op_sel_hi:[1,0]
	v_pk_fma_f32 v[42:43], v[4:5], v[142:143], v[42:43] op_sel:[0,1,0]
	v_pk_fma_f32 v[16:17], v[20:21], v[132:133], v[38:39] op_sel:[0,1,0]
	v_pk_fma_f32 v[44:45], v[12:13], v[146:147], v[44:45] op_sel:[0,1,0]
	v_pk_fma_f32 v[42:43], v[6:7], v[144:145], v[42:43] op_sel_hi:[1,0,1]
	v_pk_fma_f32 v[44:45], v[14:15], v[148:149], v[44:45] op_sel_hi:[1,0,1]
	v_pk_fma_f32 v[42:43], v[8:9], v[144:145], v[42:43] op_sel:[0,1,0]
	v_pk_fma_f32 v[44:45], v[16:17], v[148:149], v[44:45] op_sel:[0,1,0]
	v_pk_add_f32 v[42:43], v[42:43], v[44:45]
	s_nop 1
	v_add_f32_dpp v42, v42, v42 quad_perm:[1,0,3,2] row_mask:0xf bank_mask:0xf bound_ctrl:1
	v_add_f32_dpp v43, v43, v43 quad_perm:[1,0,3,2] row_mask:0xf bank_mask:0xf bound_ctrl:1
	s_nop 0
	v_add_f32_dpp v42, v42, v42 quad_perm:[2,3,0,1] row_mask:0xf bank_mask:0xf bound_ctrl:1
	v_add_f32_dpp v43, v43, v43 quad_perm:[2,3,0,1] row_mask:0xf bank_mask:0xf bound_ctrl:1
	s_nop 0
	v_add_f32_dpp v42, v42, v42 row_half_mirror row_mask:0xf bank_mask:0xf bound_ctrl:1
	v_add_f32_dpp v43, v43, v43 row_half_mirror row_mask:0xf bank_mask:0xf bound_ctrl:1
	ds_write_b64 v184, v[42:43] offset:32512
	s_waitcnt lgkmcnt(0)
	s_barrier
	v_swap_b32 v180, v186
	v_swap_b32 v181, v187
	v_swap_b32 v184, v188
	s_add_i32 s1, s1, 1
	s_cmpk_eq_i32 s1, 0x100
	s_cbranch_scc0 .Lrk_scan_loop
	s_setprio 0
	s_branch .LBB0_156
